# GEMM prefetch loads issued after the third MFMA group
# baseline (speedup 1.0000x reference)
; __device__ __forceinline__ void gemm_kstep(const u16* sb, int wn, int wt, int r, int h, f32x16 (&acc)[2][2]) {
;   const u16* bw = sb + (wn * 64 + r) * LDT + h * 8;
;   const u16* bx = sb + TILE_U16 + (wt * 64 + r) * LDT + h * 8;
;   __builtin_amdgcn_s_setprio(1);
; #pragma unroll
;   for (int ks = 0; ks < 4; ++ks) {
;     bf16x8 a0 = *(const bf16x8*)(bw + ks * 16);
;     bf16x8 a1 = *(const bf16x8*)(bw + 32 * LDT + ks * 16);
;     bf16x8 b0 = *(const bf16x8*)(bx + ks * 16);
;     bf16x8 b1 = *(const bf16x8*)(bx + 32 * LDT + ks * 16);
;     acc[0][0] = mfma32(a0, b0, acc[0][0]);
;     acc[0][1] = mfma32(a0, b1, acc[0][1]);
;     acc[1][0] = mfma32(a1, b0, acc[1][0]);
;     acc[1][1] = mfma32(a1, b1, acc[1][1]);
;   }
;   __builtin_amdgcn_s_setprio(0);
; }
; __device__ void gemm_phase(const u16* __restrict__ Wb, int ldw, const u16* __restrict__ Xb, int ldx, int K,
;                            u16* __restrict__ outb, int ldo, int ntn, int ntiles, u16* lds) {
;     ...
;   for (; q < L; q += nbl) {
;     const int qn = q + nbl;
;     const bool has_next = qn < L;
;     const int qq = has_next ? qn : q;
;     const u16* gwn = Wb + (size_t)(GP_NT(qq) * 128 + lrow) * ldw + lc * 8;
;     const u16* gxn = Xb + (size_t)(GP_MT(qq) * 128 + lrow) * ldx + lc * 8;
;     f32x16 acc[2][2];
; #pragma unroll
;     for (int a = 0; a < 2; ++a)
; #pragma unroll
;       for (int b = 0; b < 2; ++b)
; #pragma unroll
;         for (int i = 0; i < 16; ++i) acc[a][b][i] = 0.f;
;     gs_store(B, lds, lo);
;     __syncthreads();
;     for (int kt = 0; kt < nk; kt += 2) {
;       if (kt + 2 < nk) gs_load(B, gw, ldw, gx, ldx, (kt + 2) * 64);
;       else if (has_next) gs_load(B, gwn, ldw, gxn, ldx, 0);
;       gemm_kstep(lds, wn, wt, r, h, acc);
;       gs_store(A, lds + 2 * TILE_U16, lo);
;       __syncthreads();
.LBB0_598:
	v_mov_b64_e32 v[160:161], v[132:133]
	v_add_co_u32_e32 v162, vcc, s81, v160
	v_mov_b64_e32 v[158:159], v[134:135]
	s_nop 0
	v_addc_co_u32_e32 v163, vcc, 0, v161, vcc
	v_add_co_u32_e32 v164, vcc, s80, v160
	s_waitcnt vmcnt(1)
	ds_write_b128 v188, v[98:101]
	ds_write_b128 v188, v[102:105] offset:4608
	ds_write_b128 v188, v[106:109] offset:9216
	ds_write_b128 v188, v[110:113] offset:13824
	ds_write_b128 v188, v[114:117] offset:18432
	ds_write_b128 v188, v[118:121] offset:23040
	ds_write_b128 v188, v[122:125] offset:27648
	ds_write_b128 v188, v[126:129] offset:32256
	v_addc_co_u32_e32 v165, vcc, 0, v161, vcc
	v_add_co_u32_e32 v166, vcc, s84, v160
	s_waitcnt lgkmcnt(0)
	s_nop 0
	v_addc_co_u32_e32 v167, vcc, 0, v161, vcc
	v_add_co_u32_e32 v168, vcc, s81, v158
	s_barrier
	s_nop 0
	v_addc_co_u32_e32 v169, vcc, 0, v159, vcc
	v_add_co_u32_e32 v170, vcc, s80, v158
	s_nop 1
	v_addc_co_u32_e32 v171, vcc, 0, v159, vcc
	v_add_co_u32_e32 v172, vcc, s84, v158
	global_load_dwordx4 v[98:101], v[160:161], off offset:256
	global_load_dwordx4 v[102:105], v[162:163], off offset:256
	v_addc_co_u32_e32 v173, vcc, 0, v159, vcc
	global_load_dwordx4 v[106:109], v[164:165], off offset:256
	global_load_dwordx4 v[110:113], v[166:167], off offset:256
	global_load_dwordx4 v[114:117], v[158:159], off offset:256
	global_load_dwordx4 v[118:121], v[168:169], off offset:256
	global_load_dwordx4 v[122:125], v[170:171], off offset:256
	global_load_dwordx4 v[126:129], v[172:173], off offset:256
	s_add_i32 s38, s39, s87
	s_cmpk_gt_u32 s38, 0x23f
	s_cselect_b64 s[16:17], -1, 0
	s_cmpk_lt_u32 s38, 0x240
	s_cselect_b64 s[0:1], -1, 0
	s_and_b64 s[40:41], s[0:1], exec
	s_cselect_b32 s40, s38, s39
	s_mul_hi_u32 s41, s40, 0x38e38e39
	s_lshr_b32 s41, s41, 5
	s_mul_i32 s44, s41, 0x90
	s_sub_i32 s40, s40, s44
	s_lshl_b32 s44, s40, 4
	s_and_b32 s40, s40, 7
	s_or_b32 s40, s40, s18
	s_lshl_b32 s41, s41, 10
	s_lshl_b32 s40, s40, 7
	s_and_b32 s44, s44, 0xf80
	s_add_i32 s40, s40, s41
	v_add_u32_e32 v2, s44, v131
	v_add_u32_e32 v4, s40, v131
	v_ashrrev_i32_e32 v3, 31, v2
	v_ashrrev_i32_e32 v5, 31, v4
	v_lshlrev_b64 v[2:3], 11, v[2:3]
	v_lshlrev_b64 v[4:5], 11, v[4:5]
	v_lshl_add_u64 v[132:133], v[136:137], 0, v[2:3]
	v_lshl_add_u64 v[134:135], v[138:139], 0, v[4:5]
	s_setprio 1
	ds_read_b128 v[2:5], v140
	ds_read_b128 v[6:9], v141 offset:18432
	ds_read_b128 v[10:13], v141 offset:23040
	s_waitcnt lgkmcnt(1)
	v_mfma_f32_32x32x16_bf16 v[50:65], v[2:5], v[6:9], 0
	s_waitcnt lgkmcnt(0)
	v_mfma_f32_32x32x16_bf16 v[34:49], v[2:5], v[10:13], 0
	ds_read_b128 v[2:5], v140 offset:4608
	ds_read_b128 v[198:201], v140 offset:32
	ds_read_b128 v[202:205], v141 offset:18464
	ds_read_b128 v[206:209], v141 offset:23072
	s_waitcnt lgkmcnt(1)
	v_mfma_f32_32x32x16_bf16 v[50:65], v[198:201], v[202:205], v[50:65]
	s_waitcnt lgkmcnt(0)
	v_mfma_f32_32x32x16_bf16 v[34:49], v[198:201], v[206:209], v[34:49]
	ds_read_b128 v[198:201], v140 offset:4640
	v_mfma_f32_32x32x16_bf16 v[18:33], v[2:5], v[6:9], 0
	v_mfma_f32_32x32x16_bf16 v[2:17], v[2:5], v[10:13], 0
	s_waitcnt lgkmcnt(0)
	v_mfma_f32_32x32x16_bf16 v[18:33], v[198:201], v[202:205], v[18:33]
	v_mfma_f32_32x32x16_bf16 v[2:17], v[198:201], v[206:209], v[2:17]
	ds_read_b128 v[198:201], v140 offset:64
	ds_read_b128 v[202:205], v141 offset:18496
	ds_read_b128 v[206:209], v141 offset:23104
	s_waitcnt lgkmcnt(1)
	v_mfma_f32_32x32x16_bf16 v[50:65], v[198:201], v[202:205], v[50:65]
	s_waitcnt lgkmcnt(0)
	v_mfma_f32_32x32x16_bf16 v[34:49], v[198:201], v[206:209], v[34:49]
	ds_read_b128 v[198:201], v140 offset:4672
	s_waitcnt lgkmcnt(0)
	v_mfma_f32_32x32x16_bf16 v[18:33], v[198:201], v[202:205], v[18:33]
	v_mfma_f32_32x32x16_bf16 v[2:17], v[198:201], v[206:209], v[2:17]
	ds_read_b128 v[198:201], v140 offset:96
	ds_read_b128 v[202:205], v141 offset:18528
	ds_read_b128 v[206:209], v141 offset:23136
	s_waitcnt lgkmcnt(1)
	v_mfma_f32_32x32x16_bf16 v[50:65], v[198:201], v[202:205], v[50:65]
	s_waitcnt lgkmcnt(0)
	v_mfma_f32_32x32x16_bf16 v[34:49], v[198:201], v[206:209], v[34:49]
	ds_read_b128 v[198:201], v140 offset:4704
	s_waitcnt lgkmcnt(0)
	v_mfma_f32_32x32x16_bf16 v[18:33], v[198:201], v[202:205], v[18:33]
	v_mfma_f32_32x32x16_bf16 v[2:17], v[198:201], v[206:209], v[2:17]
	s_setprio 0
	ds_write_b128 v188, v[66:69] offset:36864
	ds_write_b128 v188, v[70:73] offset:41472
	ds_write_b128 v188, v[74:77] offset:46080
	ds_write_b128 v188, v[78:81] offset:50688
	ds_write_b128 v188, v[82:85] offset:55296
	ds_write_b128 v188, v[86:89] offset:59904
	ds_write_b128 v188, v[90:93] offset:64512
	s_waitcnt vmcnt(8)
	ds_write_b128 v189, v[94:97] offset:13824
	s_waitcnt lgkmcnt(0)
	s_barrier
; __device__ __forceinline__ void gemm_kstep(const u16* sb, int wn, int wt, int r, int h, f32x16 (&acc)[2][2]) {
;   const u16* bw = sb + (wn * 64 + r) * LDT + h * 8;
;   const u16* bx = sb + TILE_U16 + (wt * 64 + r) * LDT + h * 8;
;   __builtin_amdgcn_s_setprio(1);
; #pragma unroll
;   for (int ks = 0; ks < 4; ++ks) {
;     bf16x8 a0 = *(const bf16x8*)(bw + ks * 16);
;     bf16x8 a1 = *(const bf16x8*)(bw + 32 * LDT + ks * 16);
;     bf16x8 b0 = *(const bf16x8*)(bx + ks * 16);
;     bf16x8 b1 = *(const bf16x8*)(bx + 32 * LDT + ks * 16);
;     acc[0][0] = mfma32(a0, b0, acc[0][0]);
;     acc[0][1] = mfma32(a0, b1, acc[0][1]);
;     acc[1][0] = mfma32(a1, b0, acc[1][0]);
;     acc[1][1] = mfma32(a1, b1, acc[1][1]);
;   }
;   __builtin_amdgcn_s_setprio(0);
; }
; __device__ void gemm_phase(const u16* __restrict__ Wb, int ldw, const u16* __restrict__ Xb, int ldx, int K,
;                            u16* __restrict__ outb, int ldo, int ntn, int ntiles, u16* lds) {
;     ...
;     for (int kt = 0; kt < nk; kt += 2) {
;       if (kt + 2 < nk) gs_load(B, gw, ldw, gx, ldx, (kt + 2) * 64);
;       else if (has_next) gs_load(B, gwn, ldw, gxn, ldx, 0);
;       gemm_kstep(lds, wn, wt, r, h, acc);
;       gs_store(A, lds + 2 * TILE_U16, lo);
;       __syncthreads();
;       if (kt + 3 < nk) gs_load(A, gw, ldw, gx, ldx, (kt + 3) * 64);
;       else if (has_next) gs_load(A, gwn, ldw, gxn, ldx, 64);
;       gemm_kstep(lds + 2 * TILE_U16, wn, wt, r, h, acc);
;       if (kt + 2 < nk) gs_store(B, lds, lo);
;       __syncthreads();
;     }
	s_setprio 1
	ds_read_b128 v[198:201], v140 offset:36864
	ds_read_b128 v[202:205], v141 offset:55296
	ds_read_b128 v[206:209], v141 offset:59904
	ds_read_b128 v[214:217], v140 offset:41472
	ds_read_b128 v[218:221], v140 offset:36896
	ds_read_b128 v[222:225], v141 offset:55328
	ds_read_b128 v[226:229], v141 offset:59936
	ds_read_b128 v[230:233], v140 offset:41504
	s_waitcnt lgkmcnt(4)
	v_mfma_f32_32x32x16_bf16 v[50:65], v[198:201], v[202:205], v[50:65]
	v_mfma_f32_32x32x16_bf16 v[34:49], v[198:201], v[206:209], v[34:49]
	v_mfma_f32_32x32x16_bf16 v[18:33], v[214:217], v[202:205], v[18:33]
	v_mfma_f32_32x32x16_bf16 v[2:17], v[214:217], v[206:209], v[2:17]
	ds_read_b128 v[198:201], v140 offset:36928
	ds_read_b128 v[202:205], v141 offset:55360
	ds_read_b128 v[206:209], v141 offset:59968
	ds_read_b128 v[214:217], v140 offset:41536
	s_waitcnt lgkmcnt(4)
	v_mfma_f32_32x32x16_bf16 v[50:65], v[218:221], v[222:225], v[50:65]
	v_mfma_f32_32x32x16_bf16 v[34:49], v[218:221], v[226:229], v[34:49]
	v_mfma_f32_32x32x16_bf16 v[18:33], v[230:233], v[222:225], v[18:33]
	v_mfma_f32_32x32x16_bf16 v[2:17], v[230:233], v[226:229], v[2:17]
	ds_read_b128 v[218:221], v140 offset:36960
	ds_read_b128 v[222:225], v141 offset:55392
	ds_read_b128 v[226:229], v141 offset:60000
	ds_read_b128 v[230:233], v140 offset:41568
	s_waitcnt lgkmcnt(4)
	v_mfma_f32_32x32x16_bf16 v[50:65], v[198:201], v[202:205], v[50:65]
	v_mfma_f32_32x32x16_bf16 v[34:49], v[198:201], v[206:209], v[34:49]
	v_mfma_f32_32x32x16_bf16 v[18:33], v[214:217], v[202:205], v[18:33]
	v_mfma_f32_32x32x16_bf16 v[2:17], v[214:217], v[206:209], v[2:17]
	global_load_dwordx4 v[66:69], v[160:161], off offset:384
	global_load_dwordx4 v[70:73], v[162:163], off offset:384
	global_load_dwordx4 v[74:77], v[164:165], off offset:384
	global_load_dwordx4 v[78:81], v[166:167], off offset:384
	global_load_dwordx4 v[82:85], v[158:159], off offset:384
	global_load_dwordx4 v[86:89], v[168:169], off offset:384
	global_load_dwordx4 v[90:93], v[170:171], off offset:384
	global_load_dwordx4 v[94:97], v[172:173], off offset:384
	s_waitcnt lgkmcnt(0)
	v_mfma_f32_32x32x16_bf16 v[50:65], v[218:221], v[222:225], v[50:65]
	v_mfma_f32_32x32x16_bf16 v[34:49], v[218:221], v[226:229], v[34:49]
	v_mfma_f32_32x32x16_bf16 v[18:33], v[230:233], v[222:225], v[18:33]
	v_mfma_f32_32x32x16_bf16 v[2:17], v[230:233], v[226:229], v[2:17]
	s_setprio 0
	s_waitcnt vmcnt(8)
	ds_write_b128 v188, v[98:101]
	ds_write_b128 v188, v[102:105] offset:4608
	ds_write_b128 v188, v[106:109] offset:9216
	ds_write_b128 v188, v[110:113] offset:13824
	ds_write_b128 v188, v[114:117] offset:18432
	ds_write_b128 v188, v[118:121] offset:23040
	ds_write_b128 v188, v[122:125] offset:27648
	ds_write_b128 v188, v[126:129] offset:32256
	s_waitcnt lgkmcnt(0)
	s_barrier
	s_setprio 1
	ds_read_b128 v[198:201], v140
	ds_read_b128 v[202:205], v141 offset:18432
	ds_read_b128 v[206:209], v141 offset:23040
	ds_read_b128 v[214:217], v140 offset:4608
	ds_read_b128 v[218:221], v140 offset:32
	ds_read_b128 v[222:225], v141 offset:18464
	ds_read_b128 v[226:229], v141 offset:23072
	ds_read_b128 v[230:233], v140 offset:4640
	s_waitcnt lgkmcnt(4)
	v_mfma_f32_32x32x16_bf16 v[50:65], v[198:201], v[202:205], v[50:65]
	v_mfma_f32_32x32x16_bf16 v[34:49], v[198:201], v[206:209], v[34:49]
	v_mfma_f32_32x32x16_bf16 v[18:33], v[214:217], v[202:205], v[18:33]
	v_mfma_f32_32x32x16_bf16 v[2:17], v[214:217], v[206:209], v[2:17]
	ds_read_b128 v[198:201], v140 offset:64
	ds_read_b128 v[202:205], v141 offset:18496
	ds_read_b128 v[206:209], v141 offset:23104
	ds_read_b128 v[214:217], v140 offset:4672
	s_waitcnt lgkmcnt(4)
	v_mfma_f32_32x32x16_bf16 v[50:65], v[218:221], v[222:225], v[50:65]
	v_mfma_f32_32x32x16_bf16 v[34:49], v[218:221], v[226:229], v[34:49]
	v_mfma_f32_32x32x16_bf16 v[18:33], v[230:233], v[222:225], v[18:33]
	v_mfma_f32_32x32x16_bf16 v[2:17], v[230:233], v[226:229], v[2:17]
	ds_read_b128 v[218:221], v140 offset:96
	ds_read_b128 v[222:225], v141 offset:18528
	ds_read_b128 v[226:229], v141 offset:23136
	ds_read_b128 v[230:233], v140 offset:4704
	s_waitcnt lgkmcnt(4)
	v_mfma_f32_32x32x16_bf16 v[50:65], v[198:201], v[202:205], v[50:65]
	v_mfma_f32_32x32x16_bf16 v[34:49], v[198:201], v[206:209], v[34:49]
	v_mfma_f32_32x32x16_bf16 v[18:33], v[214:217], v[202:205], v[18:33]
	v_mfma_f32_32x32x16_bf16 v[2:17], v[214:217], v[206:209], v[2:17]
	global_load_dwordx4 v[98:101], v[160:161], off offset:512
	global_load_dwordx4 v[102:105], v[162:163], off offset:512
	global_load_dwordx4 v[106:109], v[164:165], off offset:512
	global_load_dwordx4 v[110:113], v[166:167], off offset:512
	global_load_dwordx4 v[114:117], v[158:159], off offset:512
	global_load_dwordx4 v[118:121], v[168:169], off offset:512
	global_load_dwordx4 v[122:125], v[170:171], off offset:512
	global_load_dwordx4 v[126:129], v[172:173], off offset:512
	s_waitcnt lgkmcnt(0)
	v_mfma_f32_32x32x16_bf16 v[50:65], v[218:221], v[222:225], v[50:65]
	v_mfma_f32_32x32x16_bf16 v[34:49], v[218:221], v[226:229], v[34:49]
	v_mfma_f32_32x32x16_bf16 v[18:33], v[230:233], v[222:225], v[18:33]
	v_mfma_f32_32x32x16_bf16 v[2:17], v[230:233], v[226:229], v[2:17]
	s_setprio 0
	s_waitcnt vmcnt(8)
	ds_write_b128 v188, v[66:69] offset:36864
	ds_write_b128 v188, v[70:73] offset:41472
	ds_write_b128 v188, v[74:77] offset:46080
	ds_write_b128 v188, v[78:81] offset:50688
	ds_write_b128 v188, v[82:85] offset:55296
	ds_write_b128 v188, v[86:89] offset:59904
	ds_write_b128 v188, v[90:93] offset:64512
	ds_write_b128 v189, v[94:97] offset:13824
	s_waitcnt lgkmcnt(0)
	s_barrier
; __device__ __forceinline__ void gemm_kstep(const u16* sb, int wn, int wt, int r, int h, f32x16 (&acc)[2][2]) {
;   const u16* bw = sb + (wn * 64 + r) * LDT + h * 8;
;   const u16* bx = sb + TILE_U16 + (wt * 64 + r) * LDT + h * 8;
;   __builtin_amdgcn_s_setprio(1);
; #pragma unroll
;   for (int ks = 0; ks < 4; ++ks) {
;     bf16x8 a0 = *(const bf16x8*)(bw + ks * 16);
;     bf16x8 a1 = *(const bf16x8*)(bw + 32 * LDT + ks * 16);
;     bf16x8 b0 = *(const bf16x8*)(bx + ks * 16);
;     bf16x8 b1 = *(const bf16x8*)(bx + 32 * LDT + ks * 16);
;     acc[0][0] = mfma32(a0, b0, acc[0][0]);
;     acc[0][1] = mfma32(a0, b1, acc[0][1]);
;     acc[1][0] = mfma32(a1, b0, acc[1][0]);
;     acc[1][1] = mfma32(a1, b1, acc[1][1]);
;   }
;   __builtin_amdgcn_s_setprio(0);
; }
; __device__ void gemm_phase(const u16* __restrict__ Wb, int ldw, const u16* __restrict__ Xb, int ldx, int K,
;                            u16* __restrict__ outb, int ldo, int ntn, int ntiles, u16* lds) {
;     ...
;     for (int kt = 0; kt < nk; kt += 2) {
;       if (kt + 2 < nk) gs_load(B, gw, ldw, gx, ldx, (kt + 2) * 64);
;       else if (has_next) gs_load(B, gwn, ldw, gxn, ldx, 0);
;       gemm_kstep(lds, wn, wt, r, h, acc);
;       gs_store(A, lds + 2 * TILE_U16, lo);
;       __syncthreads();
;       if (kt + 3 < nk) gs_load(A, gw, ldw, gx, ldx, (kt + 3) * 64);
;       else if (has_next) gs_load(A, gwn, ldw, gxn, ldx, 64);
;       gemm_kstep(lds + 2 * TILE_U16, wn, wt, r, h, acc);
;       if (kt + 2 < nk) gs_store(B, lds, lo);
;       __syncthreads();
;     }
	s_setprio 1
	ds_read_b128 v[198:201], v140 offset:36864
	ds_read_b128 v[202:205], v141 offset:55296
	ds_read_b128 v[206:209], v141 offset:59904
	ds_read_b128 v[214:217], v140 offset:41472
	ds_read_b128 v[218:221], v140 offset:36896
	ds_read_b128 v[222:225], v141 offset:55328
	ds_read_b128 v[226:229], v141 offset:59936
	ds_read_b128 v[230:233], v140 offset:41504
	s_waitcnt lgkmcnt(4)
	v_mfma_f32_32x32x16_bf16 v[50:65], v[198:201], v[202:205], v[50:65]
	v_mfma_f32_32x32x16_bf16 v[34:49], v[198:201], v[206:209], v[34:49]
	v_mfma_f32_32x32x16_bf16 v[18:33], v[214:217], v[202:205], v[18:33]
	v_mfma_f32_32x32x16_bf16 v[2:17], v[214:217], v[206:209], v[2:17]
	ds_read_b128 v[198:201], v140 offset:36928
	ds_read_b128 v[202:205], v141 offset:55360
	ds_read_b128 v[206:209], v141 offset:59968
	ds_read_b128 v[214:217], v140 offset:41536
	s_waitcnt lgkmcnt(4)
	v_mfma_f32_32x32x16_bf16 v[50:65], v[218:221], v[222:225], v[50:65]
	v_mfma_f32_32x32x16_bf16 v[34:49], v[218:221], v[226:229], v[34:49]
	v_mfma_f32_32x32x16_bf16 v[18:33], v[230:233], v[222:225], v[18:33]
	v_mfma_f32_32x32x16_bf16 v[2:17], v[230:233], v[226:229], v[2:17]
	ds_read_b128 v[218:221], v140 offset:36960
	ds_read_b128 v[222:225], v141 offset:55392
	ds_read_b128 v[226:229], v141 offset:60000
	ds_read_b128 v[230:233], v140 offset:41568
	s_waitcnt lgkmcnt(4)
	v_mfma_f32_32x32x16_bf16 v[50:65], v[198:201], v[202:205], v[50:65]
	v_mfma_f32_32x32x16_bf16 v[34:49], v[198:201], v[206:209], v[34:49]
	v_mfma_f32_32x32x16_bf16 v[18:33], v[214:217], v[202:205], v[18:33]
	v_mfma_f32_32x32x16_bf16 v[2:17], v[214:217], v[206:209], v[2:17]
	global_load_dwordx4 v[66:69], v[160:161], off offset:640
	global_load_dwordx4 v[70:73], v[162:163], off offset:640
	global_load_dwordx4 v[74:77], v[164:165], off offset:640
	global_load_dwordx4 v[78:81], v[166:167], off offset:640
	global_load_dwordx4 v[82:85], v[158:159], off offset:640
	global_load_dwordx4 v[86:89], v[168:169], off offset:640
	global_load_dwordx4 v[90:93], v[170:171], off offset:640
	global_load_dwordx4 v[94:97], v[172:173], off offset:640
	s_waitcnt lgkmcnt(0)
	v_mfma_f32_32x32x16_bf16 v[50:65], v[218:221], v[222:225], v[50:65]
	v_mfma_f32_32x32x16_bf16 v[34:49], v[218:221], v[226:229], v[34:49]
	v_mfma_f32_32x32x16_bf16 v[18:33], v[230:233], v[222:225], v[18:33]
	v_mfma_f32_32x32x16_bf16 v[2:17], v[230:233], v[226:229], v[2:17]
	s_setprio 0
	s_waitcnt vmcnt(8)
	ds_write_b128 v188, v[98:101]
	ds_write_b128 v188, v[102:105] offset:4608
	ds_write_b128 v188, v[106:109] offset:9216
	ds_write_b128 v188, v[110:113] offset:13824
	ds_write_b128 v188, v[114:117] offset:18432
	ds_write_b128 v188, v[118:121] offset:23040
	ds_write_b128 v188, v[122:125] offset:27648
	ds_write_b128 v188, v[126:129] offset:32256
	s_waitcnt lgkmcnt(0)
	s_barrier
	s_setprio 1
	ds_read_b128 v[198:201], v140
	ds_read_b128 v[202:205], v141 offset:18432
	ds_read_b128 v[206:209], v141 offset:23040
	ds_read_b128 v[214:217], v140 offset:4608
	ds_read_b128 v[218:221], v140 offset:32
	ds_read_b128 v[222:225], v141 offset:18464
	ds_read_b128 v[226:229], v141 offset:23072
	ds_read_b128 v[230:233], v140 offset:4640
	s_waitcnt lgkmcnt(4)
	v_mfma_f32_32x32x16_bf16 v[50:65], v[198:201], v[202:205], v[50:65]
	v_mfma_f32_32x32x16_bf16 v[34:49], v[198:201], v[206:209], v[34:49]
	v_mfma_f32_32x32x16_bf16 v[18:33], v[214:217], v[202:205], v[18:33]
	v_mfma_f32_32x32x16_bf16 v[2:17], v[214:217], v[206:209], v[2:17]
	ds_read_b128 v[198:201], v140 offset:64
	ds_read_b128 v[202:205], v141 offset:18496
	ds_read_b128 v[206:209], v141 offset:23104
	ds_read_b128 v[214:217], v140 offset:4672
	s_waitcnt lgkmcnt(4)
	v_mfma_f32_32x32x16_bf16 v[50:65], v[218:221], v[222:225], v[50:65]
	v_mfma_f32_32x32x16_bf16 v[34:49], v[218:221], v[226:229], v[34:49]
	v_mfma_f32_32x32x16_bf16 v[18:33], v[230:233], v[222:225], v[18:33]
	v_mfma_f32_32x32x16_bf16 v[2:17], v[230:233], v[226:229], v[2:17]
	ds_read_b128 v[218:221], v140 offset:96
	ds_read_b128 v[222:225], v141 offset:18528
	ds_read_b128 v[226:229], v141 offset:23136
	ds_read_b128 v[230:233], v140 offset:4704
	s_waitcnt lgkmcnt(4)
	v_mfma_f32_32x32x16_bf16 v[50:65], v[198:201], v[202:205], v[50:65]
	v_mfma_f32_32x32x16_bf16 v[34:49], v[198:201], v[206:209], v[34:49]
	v_mfma_f32_32x32x16_bf16 v[18:33], v[214:217], v[202:205], v[18:33]
	v_mfma_f32_32x32x16_bf16 v[2:17], v[214:217], v[206:209], v[2:17]
	global_load_dwordx4 v[98:101], v[160:161], off offset:768
	global_load_dwordx4 v[102:105], v[162:163], off offset:768
	global_load_dwordx4 v[106:109], v[164:165], off offset:768
	global_load_dwordx4 v[110:113], v[166:167], off offset:768
	global_load_dwordx4 v[114:117], v[158:159], off offset:768
	global_load_dwordx4 v[118:121], v[168:169], off offset:768
	global_load_dwordx4 v[122:125], v[170:171], off offset:768
	global_load_dwordx4 v[126:129], v[172:173], off offset:768
	s_waitcnt lgkmcnt(0)
	v_mfma_f32_32x32x16_bf16 v[50:65], v[218:221], v[222:225], v[50:65]
	v_mfma_f32_32x32x16_bf16 v[34:49], v[218:221], v[226:229], v[34:49]
	v_mfma_f32_32x32x16_bf16 v[18:33], v[230:233], v[222:225], v[18:33]
	v_mfma_f32_32x32x16_bf16 v[2:17], v[230:233], v[226:229], v[2:17]
	s_setprio 0
	s_waitcnt vmcnt(8)
	ds_write_b128 v188, v[66:69] offset:36864
	ds_write_b128 v188, v[70:73] offset:41472
	ds_write_b128 v188, v[74:77] offset:46080
	ds_write_b128 v188, v[78:81] offset:50688
	ds_write_b128 v188, v[82:85] offset:55296
	ds_write_b128 v188, v[86:89] offset:59904
	ds_write_b128 v188, v[90:93] offset:64512
	ds_write_b128 v189, v[94:97] offset:13824
	s_waitcnt lgkmcnt(0)
	s_barrier
; __device__ __forceinline__ void gemm_kstep(const u16* sb, int wn, int wt, int r, int h, f32x16 (&acc)[2][2]) {
;   const u16* bw = sb + (wn * 64 + r) * LDT + h * 8;
;   const u16* bx = sb + TILE_U16 + (wt * 64 + r) * LDT + h * 8;
;   __builtin_amdgcn_s_setprio(1);
; #pragma unroll
;   for (int ks = 0; ks < 4; ++ks) {
;     bf16x8 a0 = *(const bf16x8*)(bw + ks * 16);
;     bf16x8 a1 = *(const bf16x8*)(bw + 32 * LDT + ks * 16);
;     bf16x8 b0 = *(const bf16x8*)(bx + ks * 16);
;     bf16x8 b1 = *(const bf16x8*)(bx + 32 * LDT + ks * 16);
;     acc[0][0] = mfma32(a0, b0, acc[0][0]);
;     acc[0][1] = mfma32(a0, b1, acc[0][1]);
;     acc[1][0] = mfma32(a1, b0, acc[1][0]);
;     acc[1][1] = mfma32(a1, b1, acc[1][1]);
;   }
;   __builtin_amdgcn_s_setprio(0);
; }
; __device__ void gemm_phase(const u16* __restrict__ Wb, int ldw, const u16* __restrict__ Xb, int ldx, int K,
;                            u16* __restrict__ outb, int ldo, int ntn, int ntiles, u16* lds) {
;     ...
;     for (int kt = 0; kt < nk; kt += 2) {
;       if (kt + 2 < nk) gs_load(B, gw, ldw, gx, ldx, (kt + 2) * 64);
;       else if (has_next) gs_load(B, gwn, ldw, gxn, ldx, 0);
;       gemm_kstep(lds, wn, wt, r, h, acc);
;       gs_store(A, lds + 2 * TILE_U16, lo);
;       __syncthreads();
;       if (kt + 3 < nk) gs_load(A, gw, ldw, gx, ldx, (kt + 3) * 64);
;       else if (has_next) gs_load(A, gwn, ldw, gxn, ldx, 64);
;       gemm_kstep(lds + 2 * TILE_U16, wn, wt, r, h, acc);
;       if (kt + 2 < nk) gs_store(B, lds, lo);
;       __syncthreads();
;     }
	s_setprio 1
	ds_read_b128 v[198:201], v140 offset:36864
	ds_read_b128 v[202:205], v141 offset:55296
	ds_read_b128 v[206:209], v141 offset:59904
	ds_read_b128 v[214:217], v140 offset:41472
	ds_read_b128 v[218:221], v140 offset:36896
	ds_read_b128 v[222:225], v141 offset:55328
	ds_read_b128 v[226:229], v141 offset:59936
	ds_read_b128 v[230:233], v140 offset:41504
	s_waitcnt lgkmcnt(4)
	v_mfma_f32_32x32x16_bf16 v[50:65], v[198:201], v[202:205], v[50:65]
	v_mfma_f32_32x32x16_bf16 v[34:49], v[198:201], v[206:209], v[34:49]
	v_mfma_f32_32x32x16_bf16 v[18:33], v[214:217], v[202:205], v[18:33]
	v_mfma_f32_32x32x16_bf16 v[2:17], v[214:217], v[206:209], v[2:17]
	ds_read_b128 v[198:201], v140 offset:36928
	ds_read_b128 v[202:205], v141 offset:55360
	ds_read_b128 v[206:209], v141 offset:59968
	ds_read_b128 v[214:217], v140 offset:41536
	s_waitcnt lgkmcnt(4)
	v_mfma_f32_32x32x16_bf16 v[50:65], v[218:221], v[222:225], v[50:65]
	v_mfma_f32_32x32x16_bf16 v[34:49], v[218:221], v[226:229], v[34:49]
	v_mfma_f32_32x32x16_bf16 v[18:33], v[230:233], v[222:225], v[18:33]
	v_mfma_f32_32x32x16_bf16 v[2:17], v[230:233], v[226:229], v[2:17]
	ds_read_b128 v[218:221], v140 offset:36960
	ds_read_b128 v[222:225], v141 offset:55392
	ds_read_b128 v[226:229], v141 offset:60000
	ds_read_b128 v[230:233], v140 offset:41568
	s_waitcnt lgkmcnt(4)
	v_mfma_f32_32x32x16_bf16 v[50:65], v[198:201], v[202:205], v[50:65]
	v_mfma_f32_32x32x16_bf16 v[34:49], v[198:201], v[206:209], v[34:49]
	v_mfma_f32_32x32x16_bf16 v[18:33], v[214:217], v[202:205], v[18:33]
	v_mfma_f32_32x32x16_bf16 v[2:17], v[214:217], v[206:209], v[2:17]
	global_load_dwordx4 v[66:69], v[160:161], off offset:896
	global_load_dwordx4 v[70:73], v[162:163], off offset:896
	global_load_dwordx4 v[74:77], v[164:165], off offset:896
	global_load_dwordx4 v[78:81], v[166:167], off offset:896
	global_load_dwordx4 v[82:85], v[158:159], off offset:896
	global_load_dwordx4 v[86:89], v[168:169], off offset:896
	global_load_dwordx4 v[90:93], v[170:171], off offset:896
	global_load_dwordx4 v[94:97], v[172:173], off offset:896
	s_waitcnt lgkmcnt(0)
	v_mfma_f32_32x32x16_bf16 v[50:65], v[218:221], v[222:225], v[50:65]
	v_mfma_f32_32x32x16_bf16 v[34:49], v[218:221], v[226:229], v[34:49]
	v_mfma_f32_32x32x16_bf16 v[18:33], v[230:233], v[222:225], v[18:33]
	v_mfma_f32_32x32x16_bf16 v[2:17], v[230:233], v[226:229], v[2:17]
	s_setprio 0
	s_waitcnt vmcnt(8)
	ds_write_b128 v188, v[98:101]
	ds_write_b128 v188, v[102:105] offset:4608
	ds_write_b128 v188, v[106:109] offset:9216
	ds_write_b128 v188, v[110:113] offset:13824
	ds_write_b128 v188, v[114:117] offset:18432
	ds_write_b128 v188, v[118:121] offset:23040
	ds_write_b128 v188, v[122:125] offset:27648
	ds_write_b128 v188, v[126:129] offset:32256
	s_waitcnt lgkmcnt(0)
	s_barrier
	s_setprio 1
	ds_read_b128 v[198:201], v140
	ds_read_b128 v[202:205], v141 offset:18432
	ds_read_b128 v[206:209], v141 offset:23040
	ds_read_b128 v[214:217], v140 offset:4608
	ds_read_b128 v[218:221], v140 offset:32
	ds_read_b128 v[222:225], v141 offset:18464
	ds_read_b128 v[226:229], v141 offset:23072
	ds_read_b128 v[230:233], v140 offset:4640
	s_waitcnt lgkmcnt(4)
	v_mfma_f32_32x32x16_bf16 v[50:65], v[198:201], v[202:205], v[50:65]
	v_mfma_f32_32x32x16_bf16 v[34:49], v[198:201], v[206:209], v[34:49]
	v_mfma_f32_32x32x16_bf16 v[18:33], v[214:217], v[202:205], v[18:33]
	v_mfma_f32_32x32x16_bf16 v[2:17], v[214:217], v[206:209], v[2:17]
	ds_read_b128 v[198:201], v140 offset:64
	ds_read_b128 v[202:205], v141 offset:18496
	ds_read_b128 v[206:209], v141 offset:23104
	ds_read_b128 v[214:217], v140 offset:4672
	s_waitcnt lgkmcnt(4)
	v_mfma_f32_32x32x16_bf16 v[50:65], v[218:221], v[222:225], v[50:65]
	v_mfma_f32_32x32x16_bf16 v[34:49], v[218:221], v[226:229], v[34:49]
	v_mfma_f32_32x32x16_bf16 v[18:33], v[230:233], v[222:225], v[18:33]
	v_mfma_f32_32x32x16_bf16 v[2:17], v[230:233], v[226:229], v[2:17]
	ds_read_b128 v[218:221], v140 offset:96
	ds_read_b128 v[222:225], v141 offset:18528
	ds_read_b128 v[226:229], v141 offset:23136
	ds_read_b128 v[230:233], v140 offset:4704
	s_waitcnt lgkmcnt(4)
	v_mfma_f32_32x32x16_bf16 v[50:65], v[198:201], v[202:205], v[50:65]
	v_mfma_f32_32x32x16_bf16 v[34:49], v[198:201], v[206:209], v[34:49]
	v_mfma_f32_32x32x16_bf16 v[18:33], v[214:217], v[202:205], v[18:33]
	v_mfma_f32_32x32x16_bf16 v[2:17], v[214:217], v[206:209], v[2:17]
	global_load_dwordx4 v[98:101], v[160:161], off offset:1024
	global_load_dwordx4 v[102:105], v[162:163], off offset:1024
	global_load_dwordx4 v[106:109], v[164:165], off offset:1024
	global_load_dwordx4 v[110:113], v[166:167], off offset:1024
	global_load_dwordx4 v[114:117], v[158:159], off offset:1024
	global_load_dwordx4 v[118:121], v[168:169], off offset:1024
	global_load_dwordx4 v[122:125], v[170:171], off offset:1024
	global_load_dwordx4 v[126:129], v[172:173], off offset:1024
	s_waitcnt lgkmcnt(0)
	v_mfma_f32_32x32x16_bf16 v[50:65], v[218:221], v[222:225], v[50:65]
	v_mfma_f32_32x32x16_bf16 v[34:49], v[218:221], v[226:229], v[34:49]
	v_mfma_f32_32x32x16_bf16 v[18:33], v[230:233], v[222:225], v[18:33]
	v_mfma_f32_32x32x16_bf16 v[2:17], v[230:233], v[226:229], v[2:17]
	s_setprio 0
	s_waitcnt vmcnt(8)
	ds_write_b128 v188, v[66:69] offset:36864
	ds_write_b128 v188, v[70:73] offset:41472
	ds_write_b128 v188, v[74:77] offset:46080
	ds_write_b128 v188, v[78:81] offset:50688
	ds_write_b128 v188, v[82:85] offset:55296
	ds_write_b128 v188, v[86:89] offset:59904
	ds_write_b128 v188, v[90:93] offset:64512
	ds_write_b128 v189, v[94:97] offset:13824
	s_waitcnt lgkmcnt(0)
	s_barrier
; __device__ __forceinline__ void gemm_kstep(const u16* sb, int wn, int wt, int r, int h, f32x16 (&acc)[2][2]) {
;   const u16* bw = sb + (wn * 64 + r) * LDT + h * 8;
;   const u16* bx = sb + TILE_U16 + (wt * 64 + r) * LDT + h * 8;
;   __builtin_amdgcn_s_setprio(1);
; #pragma unroll
;   for (int ks = 0; ks < 4; ++ks) {
;     bf16x8 a0 = *(const bf16x8*)(bw + ks * 16);
;     bf16x8 a1 = *(const bf16x8*)(bw + 32 * LDT + ks * 16);
;     bf16x8 b0 = *(const bf16x8*)(bx + ks * 16);
;     bf16x8 b1 = *(const bf16x8*)(bx + 32 * LDT + ks * 16);
;     acc[0][0] = mfma32(a0, b0, acc[0][0]);
;     acc[0][1] = mfma32(a0, b1, acc[0][1]);
;     acc[1][0] = mfma32(a1, b0, acc[1][0]);
;     acc[1][1] = mfma32(a1, b1, acc[1][1]);
;   }
;   __builtin_amdgcn_s_setprio(0);
; }
; __device__ void gemm_phase(const u16* __restrict__ Wb, int ldw, const u16* __restrict__ Xb, int ldx, int K,
;                            u16* __restrict__ outb, int ldo, int ntn, int ntiles, u16* lds) {
;     ...
;     for (int kt = 0; kt < nk; kt += 2) {
;       if (kt + 2 < nk) gs_load(B, gw, ldw, gx, ldx, (kt + 2) * 64);
;       else if (has_next) gs_load(B, gwn, ldw, gxn, ldx, 0);
;       gemm_kstep(lds, wn, wt, r, h, acc);
;       gs_store(A, lds + 2 * TILE_U16, lo);
;       __syncthreads();
;       if (kt + 3 < nk) gs_load(A, gw, ldw, gx, ldx, (kt + 3) * 64);
;       else if (has_next) gs_load(A, gwn, ldw, gxn, ldx, 64);
;       gemm_kstep(lds + 2 * TILE_U16, wn, wt, r, h, acc);
;       if (kt + 2 < nk) gs_store(B, lds, lo);
;       __syncthreads();
;     }
	s_setprio 1
	ds_read_b128 v[198:201], v140 offset:36864
	ds_read_b128 v[202:205], v141 offset:55296
	ds_read_b128 v[206:209], v141 offset:59904
	ds_read_b128 v[214:217], v140 offset:41472
	ds_read_b128 v[218:221], v140 offset:36896
	ds_read_b128 v[222:225], v141 offset:55328
	ds_read_b128 v[226:229], v141 offset:59936
	ds_read_b128 v[230:233], v140 offset:41504
	s_waitcnt lgkmcnt(4)
	v_mfma_f32_32x32x16_bf16 v[50:65], v[198:201], v[202:205], v[50:65]
	v_mfma_f32_32x32x16_bf16 v[34:49], v[198:201], v[206:209], v[34:49]
	v_mfma_f32_32x32x16_bf16 v[18:33], v[214:217], v[202:205], v[18:33]
	v_mfma_f32_32x32x16_bf16 v[2:17], v[214:217], v[206:209], v[2:17]
	ds_read_b128 v[198:201], v140 offset:36928
	ds_read_b128 v[202:205], v141 offset:55360
	ds_read_b128 v[206:209], v141 offset:59968
	ds_read_b128 v[214:217], v140 offset:41536
	s_waitcnt lgkmcnt(4)
	v_mfma_f32_32x32x16_bf16 v[50:65], v[218:221], v[222:225], v[50:65]
	v_mfma_f32_32x32x16_bf16 v[34:49], v[218:221], v[226:229], v[34:49]
	v_mfma_f32_32x32x16_bf16 v[18:33], v[230:233], v[222:225], v[18:33]
	v_mfma_f32_32x32x16_bf16 v[2:17], v[230:233], v[226:229], v[2:17]
	ds_read_b128 v[218:221], v140 offset:36960
	ds_read_b128 v[222:225], v141 offset:55392
	ds_read_b128 v[226:229], v141 offset:60000
	ds_read_b128 v[230:233], v140 offset:41568
	s_waitcnt lgkmcnt(4)
	v_mfma_f32_32x32x16_bf16 v[50:65], v[198:201], v[202:205], v[50:65]
	v_mfma_f32_32x32x16_bf16 v[34:49], v[198:201], v[206:209], v[34:49]
	v_mfma_f32_32x32x16_bf16 v[18:33], v[214:217], v[202:205], v[18:33]
	v_mfma_f32_32x32x16_bf16 v[2:17], v[214:217], v[206:209], v[2:17]
	global_load_dwordx4 v[66:69], v[160:161], off offset:1152
	global_load_dwordx4 v[70:73], v[162:163], off offset:1152
	global_load_dwordx4 v[74:77], v[164:165], off offset:1152
	global_load_dwordx4 v[78:81], v[166:167], off offset:1152
	global_load_dwordx4 v[82:85], v[158:159], off offset:1152
	global_load_dwordx4 v[86:89], v[168:169], off offset:1152
	global_load_dwordx4 v[90:93], v[170:171], off offset:1152
	global_load_dwordx4 v[94:97], v[172:173], off offset:1152
	s_waitcnt lgkmcnt(0)
	v_mfma_f32_32x32x16_bf16 v[50:65], v[218:221], v[222:225], v[50:65]
	v_mfma_f32_32x32x16_bf16 v[34:49], v[218:221], v[226:229], v[34:49]
	v_mfma_f32_32x32x16_bf16 v[18:33], v[230:233], v[222:225], v[18:33]
	v_mfma_f32_32x32x16_bf16 v[2:17], v[230:233], v[226:229], v[2:17]
	s_setprio 0
	s_waitcnt vmcnt(8)
	ds_write_b128 v188, v[98:101]
	ds_write_b128 v188, v[102:105] offset:4608
	ds_write_b128 v188, v[106:109] offset:9216
	ds_write_b128 v188, v[110:113] offset:13824
	ds_write_b128 v188, v[114:117] offset:18432
	ds_write_b128 v188, v[118:121] offset:23040
	ds_write_b128 v188, v[122:125] offset:27648
	ds_write_b128 v188, v[126:129] offset:32256
	s_waitcnt lgkmcnt(0)
	s_barrier
	s_setprio 1
	ds_read_b128 v[198:201], v140
	ds_read_b128 v[202:205], v141 offset:18432
	ds_read_b128 v[206:209], v141 offset:23040
	ds_read_b128 v[214:217], v140 offset:4608
	ds_read_b128 v[218:221], v140 offset:32
	ds_read_b128 v[222:225], v141 offset:18464
	ds_read_b128 v[226:229], v141 offset:23072
	ds_read_b128 v[230:233], v140 offset:4640
	s_waitcnt lgkmcnt(4)
	v_mfma_f32_32x32x16_bf16 v[50:65], v[198:201], v[202:205], v[50:65]
	v_mfma_f32_32x32x16_bf16 v[34:49], v[198:201], v[206:209], v[34:49]
	v_mfma_f32_32x32x16_bf16 v[18:33], v[214:217], v[202:205], v[18:33]
	v_mfma_f32_32x32x16_bf16 v[2:17], v[214:217], v[206:209], v[2:17]
	ds_read_b128 v[198:201], v140 offset:64
	ds_read_b128 v[202:205], v141 offset:18496
	ds_read_b128 v[206:209], v141 offset:23104
	ds_read_b128 v[214:217], v140 offset:4672
	s_waitcnt lgkmcnt(4)
	v_mfma_f32_32x32x16_bf16 v[50:65], v[218:221], v[222:225], v[50:65]
	v_mfma_f32_32x32x16_bf16 v[34:49], v[218:221], v[226:229], v[34:49]
	v_mfma_f32_32x32x16_bf16 v[18:33], v[230:233], v[222:225], v[18:33]
	v_mfma_f32_32x32x16_bf16 v[2:17], v[230:233], v[226:229], v[2:17]
	ds_read_b128 v[218:221], v140 offset:96
	ds_read_b128 v[222:225], v141 offset:18528
	ds_read_b128 v[226:229], v141 offset:23136
	ds_read_b128 v[230:233], v140 offset:4704
	s_waitcnt lgkmcnt(4)
	v_mfma_f32_32x32x16_bf16 v[50:65], v[198:201], v[202:205], v[50:65]
	v_mfma_f32_32x32x16_bf16 v[34:49], v[198:201], v[206:209], v[34:49]
	v_mfma_f32_32x32x16_bf16 v[18:33], v[214:217], v[202:205], v[18:33]
	v_mfma_f32_32x32x16_bf16 v[2:17], v[214:217], v[206:209], v[2:17]
	global_load_dwordx4 v[98:101], v[160:161], off offset:1280
	global_load_dwordx4 v[102:105], v[162:163], off offset:1280
	global_load_dwordx4 v[106:109], v[164:165], off offset:1280
	global_load_dwordx4 v[110:113], v[166:167], off offset:1280
	global_load_dwordx4 v[114:117], v[158:159], off offset:1280
	global_load_dwordx4 v[118:121], v[168:169], off offset:1280
	global_load_dwordx4 v[122:125], v[170:171], off offset:1280
	global_load_dwordx4 v[126:129], v[172:173], off offset:1280
	s_waitcnt lgkmcnt(0)
	v_mfma_f32_32x32x16_bf16 v[50:65], v[218:221], v[222:225], v[50:65]
	v_mfma_f32_32x32x16_bf16 v[34:49], v[218:221], v[226:229], v[34:49]
	v_mfma_f32_32x32x16_bf16 v[18:33], v[230:233], v[222:225], v[18:33]
	v_mfma_f32_32x32x16_bf16 v[2:17], v[230:233], v[226:229], v[2:17]
	s_setprio 0
	s_waitcnt vmcnt(8)
	ds_write_b128 v188, v[66:69] offset:36864
	ds_write_b128 v188, v[70:73] offset:41472
	ds_write_b128 v188, v[74:77] offset:46080
	ds_write_b128 v188, v[78:81] offset:50688
	ds_write_b128 v188, v[82:85] offset:55296
	ds_write_b128 v188, v[86:89] offset:59904
	ds_write_b128 v188, v[90:93] offset:64512
	ds_write_b128 v189, v[94:97] offset:13824
	s_waitcnt lgkmcnt(0)
	s_barrier
; __device__ __forceinline__ void gemm_kstep(const u16* sb, int wn, int wt, int r, int h, f32x16 (&acc)[2][2]) {
;   const u16* bw = sb + (wn * 64 + r) * LDT + h * 8;
;   const u16* bx = sb + TILE_U16 + (wt * 64 + r) * LDT + h * 8;
;   __builtin_amdgcn_s_setprio(1);
; #pragma unroll
;   for (int ks = 0; ks < 4; ++ks) {
;     bf16x8 a0 = *(const bf16x8*)(bw + ks * 16);
;     bf16x8 a1 = *(const bf16x8*)(bw + 32 * LDT + ks * 16);
;     bf16x8 b0 = *(const bf16x8*)(bx + ks * 16);
;     bf16x8 b1 = *(const bf16x8*)(bx + 32 * LDT + ks * 16);
;     acc[0][0] = mfma32(a0, b0, acc[0][0]);
;     acc[0][1] = mfma32(a0, b1, acc[0][1]);
;     acc[1][0] = mfma32(a1, b0, acc[1][0]);
;     acc[1][1] = mfma32(a1, b1, acc[1][1]);
;   }
;   __builtin_amdgcn_s_setprio(0);
; }
; __device__ void gemm_phase(const u16* __restrict__ Wb, int ldw, const u16* __restrict__ Xb, int ldx, int K,
;                            u16* __restrict__ outb, int ldo, int ntn, int ntiles, u16* lds) {
;     ...
;     for (int kt = 0; kt < nk; kt += 2) {
;       if (kt + 2 < nk) gs_load(B, gw, ldw, gx, ldx, (kt + 2) * 64);
;       else if (has_next) gs_load(B, gwn, ldw, gxn, ldx, 0);
;       gemm_kstep(lds, wn, wt, r, h, acc);
;       gs_store(A, lds + 2 * TILE_U16, lo);
;       __syncthreads();
;       if (kt + 3 < nk) gs_load(A, gw, ldw, gx, ldx, (kt + 3) * 64);
;       else if (has_next) gs_load(A, gwn, ldw, gxn, ldx, 64);
;       gemm_kstep(lds + 2 * TILE_U16, wn, wt, r, h, acc);
;       if (kt + 2 < nk) gs_store(B, lds, lo);
;       __syncthreads();
;     }
	s_setprio 1
	ds_read_b128 v[198:201], v140 offset:36864
	ds_read_b128 v[202:205], v141 offset:55296
	ds_read_b128 v[206:209], v141 offset:59904
	ds_read_b128 v[214:217], v140 offset:41472
	ds_read_b128 v[218:221], v140 offset:36896
	ds_read_b128 v[222:225], v141 offset:55328
	ds_read_b128 v[226:229], v141 offset:59936
	ds_read_b128 v[230:233], v140 offset:41504
	s_waitcnt lgkmcnt(4)
	v_mfma_f32_32x32x16_bf16 v[50:65], v[198:201], v[202:205], v[50:65]
	v_mfma_f32_32x32x16_bf16 v[34:49], v[198:201], v[206:209], v[34:49]
	v_mfma_f32_32x32x16_bf16 v[18:33], v[214:217], v[202:205], v[18:33]
	v_mfma_f32_32x32x16_bf16 v[2:17], v[214:217], v[206:209], v[2:17]
	ds_read_b128 v[198:201], v140 offset:36928
	ds_read_b128 v[202:205], v141 offset:55360
	ds_read_b128 v[206:209], v141 offset:59968
	ds_read_b128 v[214:217], v140 offset:41536
	s_waitcnt lgkmcnt(4)
	v_mfma_f32_32x32x16_bf16 v[50:65], v[218:221], v[222:225], v[50:65]
	v_mfma_f32_32x32x16_bf16 v[34:49], v[218:221], v[226:229], v[34:49]
	v_mfma_f32_32x32x16_bf16 v[18:33], v[230:233], v[222:225], v[18:33]
	v_mfma_f32_32x32x16_bf16 v[2:17], v[230:233], v[226:229], v[2:17]
	ds_read_b128 v[218:221], v140 offset:36960
	ds_read_b128 v[222:225], v141 offset:55392
	ds_read_b128 v[226:229], v141 offset:60000
	ds_read_b128 v[230:233], v140 offset:41568
	s_waitcnt lgkmcnt(4)
	v_mfma_f32_32x32x16_bf16 v[50:65], v[198:201], v[202:205], v[50:65]
	v_mfma_f32_32x32x16_bf16 v[34:49], v[198:201], v[206:209], v[34:49]
	v_mfma_f32_32x32x16_bf16 v[18:33], v[214:217], v[202:205], v[18:33]
	v_mfma_f32_32x32x16_bf16 v[2:17], v[214:217], v[206:209], v[2:17]
	global_load_dwordx4 v[66:69], v[160:161], off offset:1408
	global_load_dwordx4 v[70:73], v[162:163], off offset:1408
	global_load_dwordx4 v[74:77], v[164:165], off offset:1408
	global_load_dwordx4 v[78:81], v[166:167], off offset:1408
	global_load_dwordx4 v[82:85], v[158:159], off offset:1408
	global_load_dwordx4 v[86:89], v[168:169], off offset:1408
	global_load_dwordx4 v[90:93], v[170:171], off offset:1408
	global_load_dwordx4 v[94:97], v[172:173], off offset:1408
	s_waitcnt lgkmcnt(0)
	v_mfma_f32_32x32x16_bf16 v[50:65], v[218:221], v[222:225], v[50:65]
	v_mfma_f32_32x32x16_bf16 v[34:49], v[218:221], v[226:229], v[34:49]
	v_mfma_f32_32x32x16_bf16 v[18:33], v[230:233], v[222:225], v[18:33]
	v_mfma_f32_32x32x16_bf16 v[2:17], v[230:233], v[226:229], v[2:17]
	s_setprio 0
	s_waitcnt vmcnt(8)
	ds_write_b128 v188, v[98:101]
	ds_write_b128 v188, v[102:105] offset:4608
	ds_write_b128 v188, v[106:109] offset:9216
	ds_write_b128 v188, v[110:113] offset:13824
	ds_write_b128 v188, v[114:117] offset:18432
	ds_write_b128 v188, v[118:121] offset:23040
	ds_write_b128 v188, v[122:125] offset:27648
	ds_write_b128 v188, v[126:129] offset:32256
	s_waitcnt lgkmcnt(0)
	s_barrier
	s_setprio 1
	ds_read_b128 v[198:201], v140
	ds_read_b128 v[202:205], v141 offset:18432
	ds_read_b128 v[206:209], v141 offset:23040
	ds_read_b128 v[214:217], v140 offset:4608
	ds_read_b128 v[218:221], v140 offset:32
	ds_read_b128 v[222:225], v141 offset:18464
	ds_read_b128 v[226:229], v141 offset:23072
	ds_read_b128 v[230:233], v140 offset:4640
	s_waitcnt lgkmcnt(4)
	v_mfma_f32_32x32x16_bf16 v[50:65], v[198:201], v[202:205], v[50:65]
	v_mfma_f32_32x32x16_bf16 v[34:49], v[198:201], v[206:209], v[34:49]
	v_mfma_f32_32x32x16_bf16 v[18:33], v[214:217], v[202:205], v[18:33]
	v_mfma_f32_32x32x16_bf16 v[2:17], v[214:217], v[206:209], v[2:17]
	ds_read_b128 v[198:201], v140 offset:64
	ds_read_b128 v[202:205], v141 offset:18496
	ds_read_b128 v[206:209], v141 offset:23104
	ds_read_b128 v[214:217], v140 offset:4672
	s_waitcnt lgkmcnt(4)
	v_mfma_f32_32x32x16_bf16 v[50:65], v[218:221], v[222:225], v[50:65]
	v_mfma_f32_32x32x16_bf16 v[34:49], v[218:221], v[226:229], v[34:49]
	v_mfma_f32_32x32x16_bf16 v[18:33], v[230:233], v[222:225], v[18:33]
	v_mfma_f32_32x32x16_bf16 v[2:17], v[230:233], v[226:229], v[2:17]
	ds_read_b128 v[218:221], v140 offset:96
	ds_read_b128 v[222:225], v141 offset:18528
	ds_read_b128 v[226:229], v141 offset:23136
	ds_read_b128 v[230:233], v140 offset:4704
	s_waitcnt lgkmcnt(4)
	v_mfma_f32_32x32x16_bf16 v[50:65], v[198:201], v[202:205], v[50:65]
	v_mfma_f32_32x32x16_bf16 v[34:49], v[198:201], v[206:209], v[34:49]
	v_mfma_f32_32x32x16_bf16 v[18:33], v[214:217], v[202:205], v[18:33]
	v_mfma_f32_32x32x16_bf16 v[2:17], v[214:217], v[206:209], v[2:17]
	global_load_dwordx4 v[98:101], v[160:161], off offset:1536
	global_load_dwordx4 v[102:105], v[162:163], off offset:1536
	global_load_dwordx4 v[106:109], v[164:165], off offset:1536
	global_load_dwordx4 v[110:113], v[166:167], off offset:1536
	global_load_dwordx4 v[114:117], v[158:159], off offset:1536
	global_load_dwordx4 v[118:121], v[168:169], off offset:1536
	global_load_dwordx4 v[122:125], v[170:171], off offset:1536
	global_load_dwordx4 v[126:129], v[172:173], off offset:1536
	s_waitcnt lgkmcnt(0)
	v_mfma_f32_32x32x16_bf16 v[50:65], v[218:221], v[222:225], v[50:65]
	v_mfma_f32_32x32x16_bf16 v[34:49], v[218:221], v[226:229], v[34:49]
	v_mfma_f32_32x32x16_bf16 v[18:33], v[230:233], v[222:225], v[18:33]
	v_mfma_f32_32x32x16_bf16 v[2:17], v[230:233], v[226:229], v[2:17]
	s_setprio 0
	s_waitcnt vmcnt(8)
	ds_write_b128 v188, v[66:69] offset:36864
	ds_write_b128 v188, v[70:73] offset:41472
	ds_write_b128 v188, v[74:77] offset:46080
	ds_write_b128 v188, v[78:81] offset:50688
	ds_write_b128 v188, v[82:85] offset:55296
	ds_write_b128 v188, v[86:89] offset:59904
	ds_write_b128 v188, v[90:93] offset:64512
	ds_write_b128 v189, v[94:97] offset:13824
	s_waitcnt lgkmcnt(0)
	s_barrier
; __device__ __forceinline__ void gemm_kstep(const u16* sb, int wn, int wt, int r, int h, f32x16 (&acc)[2][2]) {
;   const u16* bw = sb + (wn * 64 + r) * LDT + h * 8;
;   const u16* bx = sb + TILE_U16 + (wt * 64 + r) * LDT + h * 8;
;   __builtin_amdgcn_s_setprio(1);
; #pragma unroll
;   for (int ks = 0; ks < 4; ++ks) {
;     bf16x8 a0 = *(const bf16x8*)(bw + ks * 16);
;     bf16x8 a1 = *(const bf16x8*)(bw + 32 * LDT + ks * 16);
;     bf16x8 b0 = *(const bf16x8*)(bx + ks * 16);
;     bf16x8 b1 = *(const bf16x8*)(bx + 32 * LDT + ks * 16);
;     acc[0][0] = mfma32(a0, b0, acc[0][0]);
;     acc[0][1] = mfma32(a0, b1, acc[0][1]);
;     acc[1][0] = mfma32(a1, b0, acc[1][0]);
;     acc[1][1] = mfma32(a1, b1, acc[1][1]);
;   }
;   __builtin_amdgcn_s_setprio(0);
; }
; __device__ void gemm_phase(const u16* __restrict__ Wb, int ldw, const u16* __restrict__ Xb, int ldx, int K,
;                            u16* __restrict__ outb, int ldo, int ntn, int ntiles, u16* lds) {
;     ...
;     for (int kt = 0; kt < nk; kt += 2) {
;       if (kt + 2 < nk) gs_load(B, gw, ldw, gx, ldx, (kt + 2) * 64);
;       else if (has_next) gs_load(B, gwn, ldw, gxn, ldx, 0);
;       gemm_kstep(lds, wn, wt, r, h, acc);
;       gs_store(A, lds + 2 * TILE_U16, lo);
;       __syncthreads();
;       if (kt + 3 < nk) gs_load(A, gw, ldw, gx, ldx, (kt + 3) * 64);
;       else if (has_next) gs_load(A, gwn, ldw, gxn, ldx, 64);
;       gemm_kstep(lds + 2 * TILE_U16, wn, wt, r, h, acc);
;       if (kt + 2 < nk) gs_store(B, lds, lo);
;       __syncthreads();
;     }
	s_setprio 1
	ds_read_b128 v[198:201], v140 offset:36864
	ds_read_b128 v[202:205], v141 offset:55296
	ds_read_b128 v[206:209], v141 offset:59904
	ds_read_b128 v[214:217], v140 offset:41472
	ds_read_b128 v[218:221], v140 offset:36896
	ds_read_b128 v[222:225], v141 offset:55328
	ds_read_b128 v[226:229], v141 offset:59936
	ds_read_b128 v[230:233], v140 offset:41504
	s_waitcnt lgkmcnt(4)
	v_mfma_f32_32x32x16_bf16 v[50:65], v[198:201], v[202:205], v[50:65]
	v_mfma_f32_32x32x16_bf16 v[34:49], v[198:201], v[206:209], v[34:49]
	v_mfma_f32_32x32x16_bf16 v[18:33], v[214:217], v[202:205], v[18:33]
	v_mfma_f32_32x32x16_bf16 v[2:17], v[214:217], v[206:209], v[2:17]
	ds_read_b128 v[198:201], v140 offset:36928
	ds_read_b128 v[202:205], v141 offset:55360
	ds_read_b128 v[206:209], v141 offset:59968
	ds_read_b128 v[214:217], v140 offset:41536
	s_waitcnt lgkmcnt(4)
	v_mfma_f32_32x32x16_bf16 v[50:65], v[218:221], v[222:225], v[50:65]
	v_mfma_f32_32x32x16_bf16 v[34:49], v[218:221], v[226:229], v[34:49]
	v_mfma_f32_32x32x16_bf16 v[18:33], v[230:233], v[222:225], v[18:33]
	v_mfma_f32_32x32x16_bf16 v[2:17], v[230:233], v[226:229], v[2:17]
	ds_read_b128 v[218:221], v140 offset:36960
	ds_read_b128 v[222:225], v141 offset:55392
	ds_read_b128 v[226:229], v141 offset:60000
	ds_read_b128 v[230:233], v140 offset:41568
	s_waitcnt lgkmcnt(4)
	v_mfma_f32_32x32x16_bf16 v[50:65], v[198:201], v[202:205], v[50:65]
	v_mfma_f32_32x32x16_bf16 v[34:49], v[198:201], v[206:209], v[34:49]
	v_mfma_f32_32x32x16_bf16 v[18:33], v[214:217], v[202:205], v[18:33]
	v_mfma_f32_32x32x16_bf16 v[2:17], v[214:217], v[206:209], v[2:17]
	global_load_dwordx4 v[66:69], v[160:161], off offset:1664
	global_load_dwordx4 v[70:73], v[162:163], off offset:1664
	global_load_dwordx4 v[74:77], v[164:165], off offset:1664
	global_load_dwordx4 v[78:81], v[166:167], off offset:1664
	global_load_dwordx4 v[82:85], v[158:159], off offset:1664
	global_load_dwordx4 v[86:89], v[168:169], off offset:1664
	global_load_dwordx4 v[90:93], v[170:171], off offset:1664
	global_load_dwordx4 v[94:97], v[172:173], off offset:1664
	s_waitcnt lgkmcnt(0)
	v_mfma_f32_32x32x16_bf16 v[50:65], v[218:221], v[222:225], v[50:65]
	v_mfma_f32_32x32x16_bf16 v[34:49], v[218:221], v[226:229], v[34:49]
	v_mfma_f32_32x32x16_bf16 v[18:33], v[230:233], v[222:225], v[18:33]
	v_mfma_f32_32x32x16_bf16 v[2:17], v[230:233], v[226:229], v[2:17]
	s_setprio 0
	s_waitcnt vmcnt(8)
	ds_write_b128 v188, v[98:101]
	ds_write_b128 v188, v[102:105] offset:4608
	ds_write_b128 v188, v[106:109] offset:9216
	ds_write_b128 v188, v[110:113] offset:13824
	ds_write_b128 v188, v[114:117] offset:18432
	ds_write_b128 v188, v[118:121] offset:23040
	ds_write_b128 v188, v[122:125] offset:27648
	ds_write_b128 v188, v[126:129] offset:32256
	s_waitcnt lgkmcnt(0)
	s_barrier
	s_setprio 1
	ds_read_b128 v[198:201], v140
	ds_read_b128 v[202:205], v141 offset:18432
	ds_read_b128 v[206:209], v141 offset:23040
	ds_read_b128 v[214:217], v140 offset:4608
	ds_read_b128 v[218:221], v140 offset:32
	ds_read_b128 v[222:225], v141 offset:18464
	ds_read_b128 v[226:229], v141 offset:23072
	ds_read_b128 v[230:233], v140 offset:4640
	s_waitcnt lgkmcnt(4)
	v_mfma_f32_32x32x16_bf16 v[50:65], v[198:201], v[202:205], v[50:65]
	v_mfma_f32_32x32x16_bf16 v[34:49], v[198:201], v[206:209], v[34:49]
	v_mfma_f32_32x32x16_bf16 v[18:33], v[214:217], v[202:205], v[18:33]
	v_mfma_f32_32x32x16_bf16 v[2:17], v[214:217], v[206:209], v[2:17]
	ds_read_b128 v[198:201], v140 offset:64
	ds_read_b128 v[202:205], v141 offset:18496
	ds_read_b128 v[206:209], v141 offset:23104
	ds_read_b128 v[214:217], v140 offset:4672
	s_waitcnt lgkmcnt(4)
	v_mfma_f32_32x32x16_bf16 v[50:65], v[218:221], v[222:225], v[50:65]
	v_mfma_f32_32x32x16_bf16 v[34:49], v[218:221], v[226:229], v[34:49]
	v_mfma_f32_32x32x16_bf16 v[18:33], v[230:233], v[222:225], v[18:33]
	v_mfma_f32_32x32x16_bf16 v[2:17], v[230:233], v[226:229], v[2:17]
	ds_read_b128 v[218:221], v140 offset:96
	ds_read_b128 v[222:225], v141 offset:18528
	ds_read_b128 v[226:229], v141 offset:23136
	ds_read_b128 v[230:233], v140 offset:4704
	s_waitcnt lgkmcnt(4)
	v_mfma_f32_32x32x16_bf16 v[50:65], v[198:201], v[202:205], v[50:65]
	v_mfma_f32_32x32x16_bf16 v[34:49], v[198:201], v[206:209], v[34:49]
	v_mfma_f32_32x32x16_bf16 v[18:33], v[214:217], v[202:205], v[18:33]
	v_mfma_f32_32x32x16_bf16 v[2:17], v[214:217], v[206:209], v[2:17]
	global_load_dwordx4 v[98:101], v[160:161], off offset:1792
	global_load_dwordx4 v[102:105], v[162:163], off offset:1792
	global_load_dwordx4 v[106:109], v[164:165], off offset:1792
	global_load_dwordx4 v[110:113], v[166:167], off offset:1792
	global_load_dwordx4 v[114:117], v[158:159], off offset:1792
	global_load_dwordx4 v[118:121], v[168:169], off offset:1792
	global_load_dwordx4 v[122:125], v[170:171], off offset:1792
	global_load_dwordx4 v[126:129], v[172:173], off offset:1792
	s_waitcnt lgkmcnt(0)
	v_mfma_f32_32x32x16_bf16 v[50:65], v[218:221], v[222:225], v[50:65]
	v_mfma_f32_32x32x16_bf16 v[34:49], v[218:221], v[226:229], v[34:49]
	v_mfma_f32_32x32x16_bf16 v[18:33], v[230:233], v[222:225], v[18:33]
	v_mfma_f32_32x32x16_bf16 v[2:17], v[230:233], v[226:229], v[2:17]
	s_setprio 0
	s_waitcnt vmcnt(8)
	ds_write_b128 v188, v[66:69] offset:36864
	ds_write_b128 v188, v[70:73] offset:41472
	ds_write_b128 v188, v[74:77] offset:46080
	ds_write_b128 v188, v[78:81] offset:50688
	ds_write_b128 v188, v[82:85] offset:55296
	ds_write_b128 v188, v[86:89] offset:59904
	ds_write_b128 v188, v[90:93] offset:64512
	ds_write_b128 v189, v[94:97] offset:13824
	s_waitcnt lgkmcnt(0)
	s_barrier
; __device__ __forceinline__ void gemm_kstep(const u16* sb, int wn, int wt, int r, int h, f32x16 (&acc)[2][2]) {
;   const u16* bw = sb + (wn * 64 + r) * LDT + h * 8;
;   const u16* bx = sb + TILE_U16 + (wt * 64 + r) * LDT + h * 8;
;   __builtin_amdgcn_s_setprio(1);
; #pragma unroll
;   for (int ks = 0; ks < 4; ++ks) {
;     bf16x8 a0 = *(const bf16x8*)(bw + ks * 16);
;     bf16x8 a1 = *(const bf16x8*)(bw + 32 * LDT + ks * 16);
;     bf16x8 b0 = *(const bf16x8*)(bx + ks * 16);
;     bf16x8 b1 = *(const bf16x8*)(bx + 32 * LDT + ks * 16);
;     acc[0][0] = mfma32(a0, b0, acc[0][0]);
;     acc[0][1] = mfma32(a0, b1, acc[0][1]);
;     acc[1][0] = mfma32(a1, b0, acc[1][0]);
;     acc[1][1] = mfma32(a1, b1, acc[1][1]);
;   }
;   __builtin_amdgcn_s_setprio(0);
; }
; __device__ void gemm_phase(const u16* __restrict__ Wb, int ldw, const u16* __restrict__ Xb, int ldx, int K,
;                            u16* __restrict__ outb, int ldo, int ntn, int ntiles, u16* lds) {
;     ...
;     for (int kt = 0; kt < nk; kt += 2) {
;       if (kt + 2 < nk) gs_load(B, gw, ldw, gx, ldx, (kt + 2) * 64);
;       else if (has_next) gs_load(B, gwn, ldw, gxn, ldx, 0);
;       gemm_kstep(lds, wn, wt, r, h, acc);
;       gs_store(A, lds + 2 * TILE_U16, lo);
;       __syncthreads();
;       if (kt + 3 < nk) gs_load(A, gw, ldw, gx, ldx, (kt + 3) * 64);
;       else if (has_next) gs_load(A, gwn, ldw, gxn, ldx, 64);
;       gemm_kstep(lds + 2 * TILE_U16, wn, wt, r, h, acc);
;       if (kt + 2 < nk) gs_store(B, lds, lo);
;       __syncthreads();
;     }
	global_load_dwordx4 v[66:69], v[160:161], off offset:1920
	global_load_dwordx4 v[70:73], v[162:163], off offset:1920
	global_load_dwordx4 v[74:77], v[164:165], off offset:1920
	global_load_dwordx4 v[78:81], v[166:167], off offset:1920
	global_load_dwordx4 v[82:85], v[158:159], off offset:1920
	global_load_dwordx4 v[86:89], v[168:169], off offset:1920
	global_load_dwordx4 v[90:93], v[170:171], off offset:1920
	global_load_dwordx4 v[94:97], v[172:173], off offset:1920
	s_setprio 1
	ds_read_b128 v[158:161], v140 offset:36864
	ds_read_b128 v[162:165], v141 offset:55296
	ds_read_b128 v[166:169], v141 offset:59904
	ds_read_b128 v[214:217], v140 offset:41472
	ds_read_b128 v[218:221], v140 offset:36896
	ds_read_b128 v[222:225], v141 offset:55328
	ds_read_b128 v[226:229], v141 offset:59936
	ds_read_b128 v[230:233], v140 offset:41504
	s_waitcnt lgkmcnt(4)
	v_mfma_f32_32x32x16_bf16 v[50:65], v[158:161], v[162:165], v[50:65]
	v_mfma_f32_32x32x16_bf16 v[34:49], v[158:161], v[166:169], v[34:49]
	v_mfma_f32_32x32x16_bf16 v[18:33], v[214:217], v[162:165], v[18:33]
	v_mfma_f32_32x32x16_bf16 v[2:17], v[214:217], v[166:169], v[2:17]
	ds_read_b128 v[158:161], v140 offset:36928
	ds_read_b128 v[162:165], v141 offset:55360
	ds_read_b128 v[166:169], v141 offset:59968
	ds_read_b128 v[214:217], v140 offset:41536
	s_waitcnt lgkmcnt(4)
	v_mfma_f32_32x32x16_bf16 v[50:65], v[218:221], v[222:225], v[50:65]
	v_mfma_f32_32x32x16_bf16 v[34:49], v[218:221], v[226:229], v[34:49]
	v_mfma_f32_32x32x16_bf16 v[18:33], v[230:233], v[222:225], v[18:33]
	v_mfma_f32_32x32x16_bf16 v[2:17], v[230:233], v[226:229], v[2:17]
	ds_read_b128 v[218:221], v140 offset:36960
	ds_read_b128 v[222:225], v141 offset:55392
	ds_read_b128 v[226:229], v141 offset:60000
	ds_read_b128 v[230:233], v140 offset:41568
	s_waitcnt lgkmcnt(4)
	v_mfma_f32_32x32x16_bf16 v[50:65], v[158:161], v[162:165], v[50:65]
	v_mfma_f32_32x32x16_bf16 v[34:49], v[158:161], v[166:169], v[34:49]
	v_mfma_f32_32x32x16_bf16 v[18:33], v[214:217], v[162:165], v[18:33]
	v_mfma_f32_32x32x16_bf16 v[2:17], v[214:217], v[166:169], v[2:17]
	s_waitcnt lgkmcnt(0)
	v_mfma_f32_32x32x16_bf16 v[50:65], v[218:221], v[222:225], v[50:65]
	v_mfma_f32_32x32x16_bf16 v[34:49], v[218:221], v[226:229], v[34:49]
	v_mfma_f32_32x32x16_bf16 v[18:33], v[230:233], v[222:225], v[18:33]
	v_mfma_f32_32x32x16_bf16 v[2:17], v[230:233], v[226:229], v[2:17]
	s_setprio 0
	s_and_b64 vcc, exec, s[16:17]
	s_waitcnt vmcnt(8)
	ds_write_b128 v188, v[98:101]
	ds_write_b128 v188, v[102:105] offset:4608
	ds_write_b128 v188, v[106:109] offset:9216
	ds_write_b128 v188, v[110:113] offset:13824
	ds_write_b128 v188, v[114:117] offset:18432
	ds_write_b128 v188, v[118:121] offset:23040
	ds_write_b128 v188, v[122:125] offset:27648
	ds_write_b128 v188, v[126:129] offset:32256
	s_waitcnt lgkmcnt(0)
	s_barrier
	s_cbranch_vccnz .LBB0_600
	v_add_co_u32_e32 v102, vcc, 0x10000, v132
	global_load_dwordx4 v[98:101], v[132:133], off
	s_nop 0
	v_addc_co_u32_e32 v103, vcc, 0, v133, vcc
	v_add_co_u32_e32 v106, vcc, 0x20000, v132
	s_nop 1
	v_addc_co_u32_e32 v107, vcc, 0, v133, vcc
	v_add_co_u32_e32 v110, vcc, 0x30000, v132
	global_load_dwordx4 v[102:105], v[102:103], off
	s_nop 0
	global_load_dwordx4 v[106:109], v[106:107], off
	v_addc_co_u32_e32 v111, vcc, 0, v133, vcc
	v_add_co_u32_e32 v118, vcc, 0x10000, v134
	global_load_dwordx4 v[110:113], v[110:111], off
	s_nop 0
	global_load_dwordx4 v[114:117], v[134:135], off
	v_addc_co_u32_e32 v119, vcc, 0, v135, vcc
	v_add_co_u32_e32 v122, vcc, 0x20000, v134
	s_nop 1
	v_addc_co_u32_e32 v123, vcc, 0, v135, vcc
	v_add_co_u32_e32 v126, vcc, 0x30000, v134
	global_load_dwordx4 v[118:121], v[118:119], off
	s_nop 0
	global_load_dwordx4 v[122:125], v[122:123], off
	v_addc_co_u32_e32 v127, vcc, 0, v135, vcc
	global_load_dwordx4 v[126:129], v[126:127], off

; __device__ __forceinline__ void gemm_kstep(const u16* sb, int wn, int wt, int r, int h, f32x16 (&acc)[2][2]) {
;   const u16* bw = sb + (wn * 64 + r) * LDT + h * 8;
;   const u16* bx = sb + TILE_U16 + (wt * 64 + r) * LDT + h * 8;
;   __builtin_amdgcn_s_setprio(1);
; #pragma unroll
;   for (int ks = 0; ks < 4; ++ks) {
;     bf16x8 a0 = *(const bf16x8*)(bw + ks * 16);
;     bf16x8 a1 = *(const bf16x8*)(bw + 32 * LDT + ks * 16);
;     bf16x8 b0 = *(const bf16x8*)(bx + ks * 16);
;     bf16x8 b1 = *(const bf16x8*)(bx + 32 * LDT + ks * 16);
;     acc[0][0] = mfma32(a0, b0, acc[0][0]);
;     acc[0][1] = mfma32(a0, b1, acc[0][1]);
;     acc[1][0] = mfma32(a1, b0, acc[1][0]);
;     acc[1][1] = mfma32(a1, b1, acc[1][1]);
;   }
;   __builtin_amdgcn_s_setprio(0);
; }
; __device__ void gemm_phase(const u16* __restrict__ Wb, int ldw, const u16* __restrict__ Xb, int ldx, int K,
;                            u16* __restrict__ outb, int ldo, int ntn, int ntiles, u16* lds) {
;     ...
;   for (; q < L; q += nbl) {
;     const int qn = q + nbl;
;     const bool has_next = qn < L;
;     const int qq = has_next ? qn : q;
;     const u16* gwn = Wb + (size_t)(GP_NT(qq) * 128 + lrow) * ldw + lc * 8;
;     const u16* gxn = Xb + (size_t)(GP_MT(qq) * 128 + lrow) * ldx + lc * 8;
;     f32x16 acc[2][2];
; #pragma unroll
;     for (int a = 0; a < 2; ++a)
; #pragma unroll
;       for (int b = 0; b < 2; ++b)
; #pragma unroll
;         for (int i = 0; i < 16; ++i) acc[a][b][i] = 0.f;
;     gs_store(B, lds, lo);
;     __syncthreads();
;     for (int kt = 0; kt < nk; kt += 2) {
;       if (kt + 2 < nk) gs_load(B, gw, ldw, gx, ldx, (kt + 2) * 64);
;       else if (has_next) gs_load(B, gwn, ldw, gxn, ldx, 0);
;       gemm_kstep(lds, wn, wt, r, h, acc);
;       gs_store(A, lds + 2 * TILE_U16, lo);
;       __syncthreads();
.LBB0_609:
	v_mov_b64_e32 v[160:161], v[132:133]
	v_add_co_u32_e32 v162, vcc, s81, v160
	v_mov_b64_e32 v[158:159], v[134:135]
	s_nop 0
	v_addc_co_u32_e32 v163, vcc, 0, v161, vcc
	v_add_co_u32_e32 v164, vcc, s80, v160
	s_waitcnt vmcnt(1)
	ds_write_b128 v188, v[86:89]
	ds_write_b128 v188, v[98:101] offset:4608
	ds_write_b128 v188, v[102:105] offset:9216
	ds_write_b128 v188, v[110:113] offset:13824
	ds_write_b128 v188, v[114:117] offset:18432
	ds_write_b128 v188, v[118:121] offset:23040
	ds_write_b128 v188, v[122:125] offset:27648
	ds_write_b128 v188, v[126:129] offset:32256
	v_addc_co_u32_e32 v165, vcc, 0, v161, vcc
	v_add_co_u32_e32 v166, vcc, s84, v160
	s_waitcnt lgkmcnt(0)
	s_nop 0
	v_addc_co_u32_e32 v167, vcc, 0, v161, vcc
	v_add_co_u32_e32 v168, vcc, s81, v158
	s_barrier
	s_nop 0
	v_addc_co_u32_e32 v169, vcc, 0, v159, vcc
	v_add_co_u32_e32 v170, vcc, s80, v158
	s_nop 1
	v_addc_co_u32_e32 v171, vcc, 0, v159, vcc
	v_add_co_u32_e32 v172, vcc, s84, v158
	global_load_dwordx4 v[86:89], v[132:133], off offset:256
	s_nop 0
	v_addc_co_u32_e32 v173, vcc, 0, v159, vcc
	global_load_dwordx4 v[98:101], v[162:163], off offset:256
	global_load_dwordx4 v[102:105], v[164:165], off offset:256
	global_load_dwordx4 v[110:113], v[166:167], off offset:256
	global_load_dwordx4 v[114:117], v[134:135], off offset:256
	global_load_dwordx4 v[118:121], v[168:169], off offset:256
	global_load_dwordx4 v[122:125], v[170:171], off offset:256
	global_load_dwordx4 v[126:129], v[172:173], off offset:256
	s_add_i32 s42, s41, s87
	s_cmpk_gt_u32 s42, 0xff
	s_cselect_b64 s[0:1], -1, 0
	s_cmpk_lt_u32 s42, 0x100
	s_cselect_b64 s[38:39], -1, 0
	s_and_b64 s[44:45], s[38:39], exec
	s_cselect_b32 s43, s42, s41
	s_lshl_b32 s44, s43, 4
	s_and_b32 s43, s43, 7
	s_or_b32 s43, s43, s18
	s_and_b32 s45, s44, 0x380
	s_and_b32 s44, s44, 0xfffffc00
	s_lshl_b32 s43, s43, 7
	s_add_i32 s43, s43, s44
	v_add_u32_e32 v2, s45, v131
	v_add_u32_e32 v4, s43, v131
	v_ashrrev_i32_e32 v3, 31, v2
	v_ashrrev_i32_e32 v5, 31, v4
	v_lshlrev_b64 v[2:3], 11, v[2:3]
	v_lshlrev_b64 v[4:5], 11, v[4:5]
	v_lshl_add_u64 v[132:133], v[136:137], 0, v[2:3]
	v_lshl_add_u64 v[134:135], v[138:139], 0, v[4:5]
	s_setprio 1
	ds_read_b128 v[2:5], v140
	ds_read_b128 v[6:9], v141 offset:18432
	ds_read_b128 v[10:13], v141 offset:23040
	s_waitcnt lgkmcnt(1)
	v_mfma_f32_32x32x16_bf16 v[50:65], v[2:5], v[6:9], 0
	s_waitcnt lgkmcnt(0)
	v_mfma_f32_32x32x16_bf16 v[34:49], v[2:5], v[10:13], 0
	ds_read_b128 v[2:5], v140 offset:4608
	ds_read_b128 v[198:201], v140 offset:32
	ds_read_b128 v[202:205], v141 offset:18464
	ds_read_b128 v[206:209], v141 offset:23072
	s_waitcnt lgkmcnt(1)
	v_mfma_f32_32x32x16_bf16 v[50:65], v[198:201], v[202:205], v[50:65]
	s_waitcnt lgkmcnt(0)
	v_mfma_f32_32x32x16_bf16 v[34:49], v[198:201], v[206:209], v[34:49]
	ds_read_b128 v[198:201], v140 offset:4640
	v_mfma_f32_32x32x16_bf16 v[18:33], v[2:5], v[6:9], 0
	v_mfma_f32_32x32x16_bf16 v[2:17], v[2:5], v[10:13], 0
	s_waitcnt lgkmcnt(0)
	v_mfma_f32_32x32x16_bf16 v[18:33], v[198:201], v[202:205], v[18:33]
	v_mfma_f32_32x32x16_bf16 v[2:17], v[198:201], v[206:209], v[2:17]
	ds_read_b128 v[198:201], v140 offset:64
	ds_read_b128 v[202:205], v141 offset:18496
	ds_read_b128 v[206:209], v141 offset:23104
	s_waitcnt lgkmcnt(1)
	v_mfma_f32_32x32x16_bf16 v[50:65], v[198:201], v[202:205], v[50:65]
	s_waitcnt lgkmcnt(0)
	v_mfma_f32_32x32x16_bf16 v[34:49], v[198:201], v[206:209], v[34:49]
	ds_read_b128 v[198:201], v140 offset:4672
	s_waitcnt lgkmcnt(0)
	v_mfma_f32_32x32x16_bf16 v[18:33], v[198:201], v[202:205], v[18:33]
	v_mfma_f32_32x32x16_bf16 v[2:17], v[198:201], v[206:209], v[2:17]
	ds_read_b128 v[198:201], v140 offset:96
	ds_read_b128 v[202:205], v141 offset:18528
	ds_read_b128 v[206:209], v141 offset:23136
	s_waitcnt lgkmcnt(1)
	v_mfma_f32_32x32x16_bf16 v[50:65], v[198:201], v[202:205], v[50:65]
	s_waitcnt lgkmcnt(0)
	v_mfma_f32_32x32x16_bf16 v[34:49], v[198:201], v[206:209], v[34:49]
	ds_read_b128 v[198:201], v140 offset:4704
	s_waitcnt lgkmcnt(0)
	v_mfma_f32_32x32x16_bf16 v[18:33], v[198:201], v[202:205], v[18:33]
	v_mfma_f32_32x32x16_bf16 v[2:17], v[198:201], v[206:209], v[2:17]
	s_setprio 0
	ds_write_b128 v188, v[66:69] offset:36864
	ds_write_b128 v188, v[70:73] offset:41472
	ds_write_b128 v188, v[74:77] offset:46080
	ds_write_b128 v188, v[78:81] offset:50688
	ds_write_b128 v188, v[82:85] offset:55296
	ds_write_b128 v188, v[90:93] offset:59904
	ds_write_b128 v188, v[94:97] offset:64512
	s_waitcnt vmcnt(8)
	ds_write_b128 v189, v[106:109] offset:13824
	s_waitcnt lgkmcnt(0)
	s_barrier
; __device__ __forceinline__ void gemm_kstep(const u16* sb, int wn, int wt, int r, int h, f32x16 (&acc)[2][2]) {
;   const u16* bw = sb + (wn * 64 + r) * LDT + h * 8;
;   const u16* bx = sb + TILE_U16 + (wt * 64 + r) * LDT + h * 8;
;   __builtin_amdgcn_s_setprio(1);
; #pragma unroll
;   for (int ks = 0; ks < 4; ++ks) {
;     bf16x8 a0 = *(const bf16x8*)(bw + ks * 16);
;     bf16x8 a1 = *(const bf16x8*)(bw + 32 * LDT + ks * 16);
;     bf16x8 b0 = *(const bf16x8*)(bx + ks * 16);
;     bf16x8 b1 = *(const bf16x8*)(bx + 32 * LDT + ks * 16);
;     acc[0][0] = mfma32(a0, b0, acc[0][0]);
;     acc[0][1] = mfma32(a0, b1, acc[0][1]);
;     acc[1][0] = mfma32(a1, b0, acc[1][0]);
;     acc[1][1] = mfma32(a1, b1, acc[1][1]);
;   }
;   __builtin_amdgcn_s_setprio(0);
; }
; __device__ void gemm_phase(const u16* __restrict__ Wb, int ldw, const u16* __restrict__ Xb, int ldx, int K,
;                            u16* __restrict__ outb, int ldo, int ntn, int ntiles, u16* lds) {
;     ...
;     for (int kt = 0; kt < nk; kt += 2) {
;       if (kt + 2 < nk) gs_load(B, gw, ldw, gx, ldx, (kt + 2) * 64);
;       else if (has_next) gs_load(B, gwn, ldw, gxn, ldx, 0);
;       gemm_kstep(lds, wn, wt, r, h, acc);
;       gs_store(A, lds + 2 * TILE_U16, lo);
;       __syncthreads();
;       if (kt + 3 < nk) gs_load(A, gw, ldw, gx, ldx, (kt + 3) * 64);
;       else if (has_next) gs_load(A, gwn, ldw, gxn, ldx, 64);
;       gemm_kstep(lds + 2 * TILE_U16, wn, wt, r, h, acc);
;       if (kt + 2 < nk) gs_store(B, lds, lo);
;       __syncthreads();
;     }
	s_setprio 1
	ds_read_b128 v[198:201], v140 offset:36864
	ds_read_b128 v[202:205], v141 offset:55296
	ds_read_b128 v[206:209], v141 offset:59904
	ds_read_b128 v[214:217], v140 offset:41472
	ds_read_b128 v[218:221], v140 offset:36896
	ds_read_b128 v[222:225], v141 offset:55328
	ds_read_b128 v[226:229], v141 offset:59936
	ds_read_b128 v[230:233], v140 offset:41504
	s_waitcnt lgkmcnt(4)
	v_mfma_f32_32x32x16_bf16 v[50:65], v[198:201], v[202:205], v[50:65]
	v_mfma_f32_32x32x16_bf16 v[34:49], v[198:201], v[206:209], v[34:49]
	v_mfma_f32_32x32x16_bf16 v[18:33], v[214:217], v[202:205], v[18:33]
	v_mfma_f32_32x32x16_bf16 v[2:17], v[214:217], v[206:209], v[2:17]
	ds_read_b128 v[198:201], v140 offset:36928
	ds_read_b128 v[202:205], v141 offset:55360
	ds_read_b128 v[206:209], v141 offset:59968
	ds_read_b128 v[214:217], v140 offset:41536
	s_waitcnt lgkmcnt(4)
	v_mfma_f32_32x32x16_bf16 v[50:65], v[218:221], v[222:225], v[50:65]
	v_mfma_f32_32x32x16_bf16 v[34:49], v[218:221], v[226:229], v[34:49]
	v_mfma_f32_32x32x16_bf16 v[18:33], v[230:233], v[222:225], v[18:33]
	v_mfma_f32_32x32x16_bf16 v[2:17], v[230:233], v[226:229], v[2:17]
	ds_read_b128 v[218:221], v140 offset:36960
	ds_read_b128 v[222:225], v141 offset:55392
	ds_read_b128 v[226:229], v141 offset:60000
	ds_read_b128 v[230:233], v140 offset:41568
	s_waitcnt lgkmcnt(4)
	v_mfma_f32_32x32x16_bf16 v[50:65], v[198:201], v[202:205], v[50:65]
	v_mfma_f32_32x32x16_bf16 v[34:49], v[198:201], v[206:209], v[34:49]
	v_mfma_f32_32x32x16_bf16 v[18:33], v[214:217], v[202:205], v[18:33]
	v_mfma_f32_32x32x16_bf16 v[2:17], v[214:217], v[206:209], v[2:17]
	global_load_dwordx4 v[66:69], v[160:161], off offset:384
	global_load_dwordx4 v[70:73], v[162:163], off offset:384
	global_load_dwordx4 v[74:77], v[164:165], off offset:384
	global_load_dwordx4 v[78:81], v[166:167], off offset:384
	global_load_dwordx4 v[82:85], v[158:159], off offset:384
	global_load_dwordx4 v[90:93], v[168:169], off offset:384
	global_load_dwordx4 v[94:97], v[170:171], off offset:384
	global_load_dwordx4 v[106:109], v[172:173], off offset:384
	s_waitcnt lgkmcnt(0)
	v_mfma_f32_32x32x16_bf16 v[50:65], v[218:221], v[222:225], v[50:65]
	v_mfma_f32_32x32x16_bf16 v[34:49], v[218:221], v[226:229], v[34:49]
	v_mfma_f32_32x32x16_bf16 v[18:33], v[230:233], v[222:225], v[18:33]
	v_mfma_f32_32x32x16_bf16 v[2:17], v[230:233], v[226:229], v[2:17]
	s_setprio 0
	s_waitcnt vmcnt(8)
	ds_write_b128 v188, v[86:89]
	ds_write_b128 v188, v[98:101] offset:4608
	ds_write_b128 v188, v[102:105] offset:9216
	ds_write_b128 v188, v[110:113] offset:13824
	ds_write_b128 v188, v[114:117] offset:18432
	ds_write_b128 v188, v[118:121] offset:23040
	ds_write_b128 v188, v[122:125] offset:27648
	ds_write_b128 v188, v[126:129] offset:32256
	s_waitcnt lgkmcnt(0)
	s_barrier
	s_setprio 1
	ds_read_b128 v[198:201], v140
	ds_read_b128 v[202:205], v141 offset:18432
	ds_read_b128 v[206:209], v141 offset:23040
	ds_read_b128 v[214:217], v140 offset:4608
	ds_read_b128 v[218:221], v140 offset:32
	ds_read_b128 v[222:225], v141 offset:18464
	ds_read_b128 v[226:229], v141 offset:23072
	ds_read_b128 v[230:233], v140 offset:4640
	s_waitcnt lgkmcnt(4)
	v_mfma_f32_32x32x16_bf16 v[50:65], v[198:201], v[202:205], v[50:65]
	v_mfma_f32_32x32x16_bf16 v[34:49], v[198:201], v[206:209], v[34:49]
	v_mfma_f32_32x32x16_bf16 v[18:33], v[214:217], v[202:205], v[18:33]
	v_mfma_f32_32x32x16_bf16 v[2:17], v[214:217], v[206:209], v[2:17]
	ds_read_b128 v[198:201], v140 offset:64
	ds_read_b128 v[202:205], v141 offset:18496
	ds_read_b128 v[206:209], v141 offset:23104
	ds_read_b128 v[214:217], v140 offset:4672
	s_waitcnt lgkmcnt(4)
	v_mfma_f32_32x32x16_bf16 v[50:65], v[218:221], v[222:225], v[50:65]
	v_mfma_f32_32x32x16_bf16 v[34:49], v[218:221], v[226:229], v[34:49]
	v_mfma_f32_32x32x16_bf16 v[18:33], v[230:233], v[222:225], v[18:33]
	v_mfma_f32_32x32x16_bf16 v[2:17], v[230:233], v[226:229], v[2:17]
	ds_read_b128 v[218:221], v140 offset:96
	ds_read_b128 v[222:225], v141 offset:18528
	ds_read_b128 v[226:229], v141 offset:23136
	ds_read_b128 v[230:233], v140 offset:4704
	s_waitcnt lgkmcnt(4)
	v_mfma_f32_32x32x16_bf16 v[50:65], v[198:201], v[202:205], v[50:65]
	v_mfma_f32_32x32x16_bf16 v[34:49], v[198:201], v[206:209], v[34:49]
	v_mfma_f32_32x32x16_bf16 v[18:33], v[214:217], v[202:205], v[18:33]
	v_mfma_f32_32x32x16_bf16 v[2:17], v[214:217], v[206:209], v[2:17]
	global_load_dwordx4 v[86:89], v[160:161], off offset:512
	global_load_dwordx4 v[98:101], v[162:163], off offset:512
	global_load_dwordx4 v[102:105], v[164:165], off offset:512
	global_load_dwordx4 v[110:113], v[166:167], off offset:512
	global_load_dwordx4 v[114:117], v[158:159], off offset:512
	global_load_dwordx4 v[118:121], v[168:169], off offset:512
	global_load_dwordx4 v[122:125], v[170:171], off offset:512
	global_load_dwordx4 v[126:129], v[172:173], off offset:512
	s_waitcnt lgkmcnt(0)
	v_mfma_f32_32x32x16_bf16 v[50:65], v[218:221], v[222:225], v[50:65]
	v_mfma_f32_32x32x16_bf16 v[34:49], v[218:221], v[226:229], v[34:49]
	v_mfma_f32_32x32x16_bf16 v[18:33], v[230:233], v[222:225], v[18:33]
	v_mfma_f32_32x32x16_bf16 v[2:17], v[230:233], v[226:229], v[2:17]
	s_setprio 0
	s_waitcnt vmcnt(8)
	ds_write_b128 v188, v[66:69] offset:36864
	ds_write_b128 v188, v[70:73] offset:41472
	ds_write_b128 v188, v[74:77] offset:46080
	ds_write_b128 v188, v[78:81] offset:50688
	ds_write_b128 v188, v[82:85] offset:55296
	ds_write_b128 v188, v[90:93] offset:59904
	ds_write_b128 v188, v[94:97] offset:64512
	ds_write_b128 v189, v[106:109] offset:13824
	s_waitcnt lgkmcnt(0)
	s_barrier
; __device__ __forceinline__ void gemm_kstep(const u16* sb, int wn, int wt, int r, int h, f32x16 (&acc)[2][2]) {
;   const u16* bw = sb + (wn * 64 + r) * LDT + h * 8;
;   const u16* bx = sb + TILE_U16 + (wt * 64 + r) * LDT + h * 8;
;   __builtin_amdgcn_s_setprio(1);
; #pragma unroll
;   for (int ks = 0; ks < 4; ++ks) {
;     bf16x8 a0 = *(const bf16x8*)(bw + ks * 16);
;     bf16x8 a1 = *(const bf16x8*)(bw + 32 * LDT + ks * 16);
;     bf16x8 b0 = *(const bf16x8*)(bx + ks * 16);
;     bf16x8 b1 = *(const bf16x8*)(bx + 32 * LDT + ks * 16);
;     acc[0][0] = mfma32(a0, b0, acc[0][0]);
;     acc[0][1] = mfma32(a0, b1, acc[0][1]);
;     acc[1][0] = mfma32(a1, b0, acc[1][0]);
;     acc[1][1] = mfma32(a1, b1, acc[1][1]);
;   }
;   __builtin_amdgcn_s_setprio(0);
; }
; __device__ void gemm_phase(const u16* __restrict__ Wb, int ldw, const u16* __restrict__ Xb, int ldx, int K,
;                            u16* __restrict__ outb, int ldo, int ntn, int ntiles, u16* lds) {
;     ...
;     for (int kt = 0; kt < nk; kt += 2) {
;       if (kt + 2 < nk) gs_load(B, gw, ldw, gx, ldx, (kt + 2) * 64);
;       else if (has_next) gs_load(B, gwn, ldw, gxn, ldx, 0);
;       gemm_kstep(lds, wn, wt, r, h, acc);
;       gs_store(A, lds + 2 * TILE_U16, lo);
;       __syncthreads();
;       if (kt + 3 < nk) gs_load(A, gw, ldw, gx, ldx, (kt + 3) * 64);
;       else if (has_next) gs_load(A, gwn, ldw, gxn, ldx, 64);
;       gemm_kstep(lds + 2 * TILE_U16, wn, wt, r, h, acc);
;       if (kt + 2 < nk) gs_store(B, lds, lo);
;       __syncthreads();
;     }
	s_setprio 1
	ds_read_b128 v[198:201], v140 offset:36864
	ds_read_b128 v[202:205], v141 offset:55296
	ds_read_b128 v[206:209], v141 offset:59904
	ds_read_b128 v[214:217], v140 offset:41472
	ds_read_b128 v[218:221], v140 offset:36896
	ds_read_b128 v[222:225], v141 offset:55328
	ds_read_b128 v[226:229], v141 offset:59936
	ds_read_b128 v[230:233], v140 offset:41504
	s_waitcnt lgkmcnt(4)
	v_mfma_f32_32x32x16_bf16 v[50:65], v[198:201], v[202:205], v[50:65]
	v_mfma_f32_32x32x16_bf16 v[34:49], v[198:201], v[206:209], v[34:49]
	v_mfma_f32_32x32x16_bf16 v[18:33], v[214:217], v[202:205], v[18:33]
	v_mfma_f32_32x32x16_bf16 v[2:17], v[214:217], v[206:209], v[2:17]
	ds_read_b128 v[198:201], v140 offset:36928
	ds_read_b128 v[202:205], v141 offset:55360
	ds_read_b128 v[206:209], v141 offset:59968
	ds_read_b128 v[214:217], v140 offset:41536
	s_waitcnt lgkmcnt(4)
	v_mfma_f32_32x32x16_bf16 v[50:65], v[218:221], v[222:225], v[50:65]
	v_mfma_f32_32x32x16_bf16 v[34:49], v[218:221], v[226:229], v[34:49]
	v_mfma_f32_32x32x16_bf16 v[18:33], v[230:233], v[222:225], v[18:33]
	v_mfma_f32_32x32x16_bf16 v[2:17], v[230:233], v[226:229], v[2:17]
	ds_read_b128 v[218:221], v140 offset:36960
	ds_read_b128 v[222:225], v141 offset:55392
	ds_read_b128 v[226:229], v141 offset:60000
	ds_read_b128 v[230:233], v140 offset:41568
	s_waitcnt lgkmcnt(4)
	v_mfma_f32_32x32x16_bf16 v[50:65], v[198:201], v[202:205], v[50:65]
	v_mfma_f32_32x32x16_bf16 v[34:49], v[198:201], v[206:209], v[34:49]
	v_mfma_f32_32x32x16_bf16 v[18:33], v[214:217], v[202:205], v[18:33]
	v_mfma_f32_32x32x16_bf16 v[2:17], v[214:217], v[206:209], v[2:17]
	global_load_dwordx4 v[66:69], v[160:161], off offset:640
	global_load_dwordx4 v[70:73], v[162:163], off offset:640
	global_load_dwordx4 v[74:77], v[164:165], off offset:640
	global_load_dwordx4 v[78:81], v[166:167], off offset:640
	global_load_dwordx4 v[82:85], v[158:159], off offset:640
	global_load_dwordx4 v[90:93], v[168:169], off offset:640
	global_load_dwordx4 v[94:97], v[170:171], off offset:640
	global_load_dwordx4 v[106:109], v[172:173], off offset:640
	s_waitcnt lgkmcnt(0)
	v_mfma_f32_32x32x16_bf16 v[50:65], v[218:221], v[222:225], v[50:65]
	v_mfma_f32_32x32x16_bf16 v[34:49], v[218:221], v[226:229], v[34:49]
	v_mfma_f32_32x32x16_bf16 v[18:33], v[230:233], v[222:225], v[18:33]
	v_mfma_f32_32x32x16_bf16 v[2:17], v[230:233], v[226:229], v[2:17]
	s_setprio 0
	s_waitcnt vmcnt(8)
	ds_write_b128 v188, v[86:89]
	ds_write_b128 v188, v[98:101] offset:4608
	ds_write_b128 v188, v[102:105] offset:9216
	ds_write_b128 v188, v[110:113] offset:13824
	ds_write_b128 v188, v[114:117] offset:18432
	ds_write_b128 v188, v[118:121] offset:23040
	ds_write_b128 v188, v[122:125] offset:27648
	ds_write_b128 v188, v[126:129] offset:32256
	s_waitcnt lgkmcnt(0)
	s_barrier
	s_setprio 1
	ds_read_b128 v[198:201], v140
	ds_read_b128 v[202:205], v141 offset:18432
	ds_read_b128 v[206:209], v141 offset:23040
	ds_read_b128 v[214:217], v140 offset:4608
	ds_read_b128 v[218:221], v140 offset:32
	ds_read_b128 v[222:225], v141 offset:18464
	ds_read_b128 v[226:229], v141 offset:23072
	ds_read_b128 v[230:233], v140 offset:4640
	s_waitcnt lgkmcnt(4)
	v_mfma_f32_32x32x16_bf16 v[50:65], v[198:201], v[202:205], v[50:65]
	v_mfma_f32_32x32x16_bf16 v[34:49], v[198:201], v[206:209], v[34:49]
	v_mfma_f32_32x32x16_bf16 v[18:33], v[214:217], v[202:205], v[18:33]
	v_mfma_f32_32x32x16_bf16 v[2:17], v[214:217], v[206:209], v[2:17]
	ds_read_b128 v[198:201], v140 offset:64
	ds_read_b128 v[202:205], v141 offset:18496
	ds_read_b128 v[206:209], v141 offset:23104
	ds_read_b128 v[214:217], v140 offset:4672
	s_waitcnt lgkmcnt(4)
	v_mfma_f32_32x32x16_bf16 v[50:65], v[218:221], v[222:225], v[50:65]
	v_mfma_f32_32x32x16_bf16 v[34:49], v[218:221], v[226:229], v[34:49]
	v_mfma_f32_32x32x16_bf16 v[18:33], v[230:233], v[222:225], v[18:33]
	v_mfma_f32_32x32x16_bf16 v[2:17], v[230:233], v[226:229], v[2:17]
	ds_read_b128 v[218:221], v140 offset:96
	ds_read_b128 v[222:225], v141 offset:18528
	ds_read_b128 v[226:229], v141 offset:23136
	ds_read_b128 v[230:233], v140 offset:4704
	s_waitcnt lgkmcnt(4)
	v_mfma_f32_32x32x16_bf16 v[50:65], v[198:201], v[202:205], v[50:65]
	v_mfma_f32_32x32x16_bf16 v[34:49], v[198:201], v[206:209], v[34:49]
	v_mfma_f32_32x32x16_bf16 v[18:33], v[214:217], v[202:205], v[18:33]
	v_mfma_f32_32x32x16_bf16 v[2:17], v[214:217], v[206:209], v[2:17]
	global_load_dwordx4 v[86:89], v[160:161], off offset:768
	global_load_dwordx4 v[98:101], v[162:163], off offset:768
	global_load_dwordx4 v[102:105], v[164:165], off offset:768
	global_load_dwordx4 v[110:113], v[166:167], off offset:768
	global_load_dwordx4 v[114:117], v[158:159], off offset:768
	global_load_dwordx4 v[118:121], v[168:169], off offset:768
	global_load_dwordx4 v[122:125], v[170:171], off offset:768
	global_load_dwordx4 v[126:129], v[172:173], off offset:768
	s_waitcnt lgkmcnt(0)
	v_mfma_f32_32x32x16_bf16 v[50:65], v[218:221], v[222:225], v[50:65]
	v_mfma_f32_32x32x16_bf16 v[34:49], v[218:221], v[226:229], v[34:49]
	v_mfma_f32_32x32x16_bf16 v[18:33], v[230:233], v[222:225], v[18:33]
	v_mfma_f32_32x32x16_bf16 v[2:17], v[230:233], v[226:229], v[2:17]
	s_setprio 0
	s_waitcnt vmcnt(8)
	ds_write_b128 v188, v[66:69] offset:36864
	ds_write_b128 v188, v[70:73] offset:41472
	ds_write_b128 v188, v[74:77] offset:46080
	ds_write_b128 v188, v[78:81] offset:50688
	ds_write_b128 v188, v[82:85] offset:55296
	ds_write_b128 v188, v[90:93] offset:59904
	ds_write_b128 v188, v[94:97] offset:64512
	ds_write_b128 v189, v[106:109] offset:13824
	s_waitcnt lgkmcnt(0)
	s_barrier
; __device__ __forceinline__ void gemm_kstep(const u16* sb, int wn, int wt, int r, int h, f32x16 (&acc)[2][2]) {
;   const u16* bw = sb + (wn * 64 + r) * LDT + h * 8;
;   const u16* bx = sb + TILE_U16 + (wt * 64 + r) * LDT + h * 8;
;   __builtin_amdgcn_s_setprio(1);
; #pragma unroll
;   for (int ks = 0; ks < 4; ++ks) {
;     bf16x8 a0 = *(const bf16x8*)(bw + ks * 16);
;     bf16x8 a1 = *(const bf16x8*)(bw + 32 * LDT + ks * 16);
;     bf16x8 b0 = *(const bf16x8*)(bx + ks * 16);
;     bf16x8 b1 = *(const bf16x8*)(bx + 32 * LDT + ks * 16);
;     acc[0][0] = mfma32(a0, b0, acc[0][0]);
;     acc[0][1] = mfma32(a0, b1, acc[0][1]);
;     acc[1][0] = mfma32(a1, b0, acc[1][0]);
;     acc[1][1] = mfma32(a1, b1, acc[1][1]);
;   }
;   __builtin_amdgcn_s_setprio(0);
; }
; __device__ void gemm_phase(const u16* __restrict__ Wb, int ldw, const u16* __restrict__ Xb, int ldx, int K,
;                            u16* __restrict__ outb, int ldo, int ntn, int ntiles, u16* lds) {
;     ...
;     for (int kt = 0; kt < nk; kt += 2) {
;       if (kt + 2 < nk) gs_load(B, gw, ldw, gx, ldx, (kt + 2) * 64);
;       else if (has_next) gs_load(B, gwn, ldw, gxn, ldx, 0);
;       gemm_kstep(lds, wn, wt, r, h, acc);
;       gs_store(A, lds + 2 * TILE_U16, lo);
;       __syncthreads();
;       if (kt + 3 < nk) gs_load(A, gw, ldw, gx, ldx, (kt + 3) * 64);
;       else if (has_next) gs_load(A, gwn, ldw, gxn, ldx, 64);
;       gemm_kstep(lds + 2 * TILE_U16, wn, wt, r, h, acc);
;       if (kt + 2 < nk) gs_store(B, lds, lo);
;       __syncthreads();
;     }
	s_setprio 1
	ds_read_b128 v[198:201], v140 offset:36864
	ds_read_b128 v[202:205], v141 offset:55296
	ds_read_b128 v[206:209], v141 offset:59904
	ds_read_b128 v[214:217], v140 offset:41472
	ds_read_b128 v[218:221], v140 offset:36896
	ds_read_b128 v[222:225], v141 offset:55328
	ds_read_b128 v[226:229], v141 offset:59936
	ds_read_b128 v[230:233], v140 offset:41504
	s_waitcnt lgkmcnt(4)
	v_mfma_f32_32x32x16_bf16 v[50:65], v[198:201], v[202:205], v[50:65]
	v_mfma_f32_32x32x16_bf16 v[34:49], v[198:201], v[206:209], v[34:49]
	v_mfma_f32_32x32x16_bf16 v[18:33], v[214:217], v[202:205], v[18:33]
	v_mfma_f32_32x32x16_bf16 v[2:17], v[214:217], v[206:209], v[2:17]
	ds_read_b128 v[198:201], v140 offset:36928
	ds_read_b128 v[202:205], v141 offset:55360
	ds_read_b128 v[206:209], v141 offset:59968
	ds_read_b128 v[214:217], v140 offset:41536
	s_waitcnt lgkmcnt(4)
	v_mfma_f32_32x32x16_bf16 v[50:65], v[218:221], v[222:225], v[50:65]
	v_mfma_f32_32x32x16_bf16 v[34:49], v[218:221], v[226:229], v[34:49]
	v_mfma_f32_32x32x16_bf16 v[18:33], v[230:233], v[222:225], v[18:33]
	v_mfma_f32_32x32x16_bf16 v[2:17], v[230:233], v[226:229], v[2:17]
	ds_read_b128 v[218:221], v140 offset:36960
	ds_read_b128 v[222:225], v141 offset:55392
	ds_read_b128 v[226:229], v141 offset:60000
	ds_read_b128 v[230:233], v140 offset:41568
	s_waitcnt lgkmcnt(4)
	v_mfma_f32_32x32x16_bf16 v[50:65], v[198:201], v[202:205], v[50:65]
	v_mfma_f32_32x32x16_bf16 v[34:49], v[198:201], v[206:209], v[34:49]
	v_mfma_f32_32x32x16_bf16 v[18:33], v[214:217], v[202:205], v[18:33]
	v_mfma_f32_32x32x16_bf16 v[2:17], v[214:217], v[206:209], v[2:17]
	global_load_dwordx4 v[66:69], v[160:161], off offset:896
	global_load_dwordx4 v[70:73], v[162:163], off offset:896
	global_load_dwordx4 v[74:77], v[164:165], off offset:896
	global_load_dwordx4 v[78:81], v[166:167], off offset:896
	global_load_dwordx4 v[82:85], v[158:159], off offset:896
	global_load_dwordx4 v[90:93], v[168:169], off offset:896
	global_load_dwordx4 v[94:97], v[170:171], off offset:896
	global_load_dwordx4 v[106:109], v[172:173], off offset:896
	s_waitcnt lgkmcnt(0)
	v_mfma_f32_32x32x16_bf16 v[50:65], v[218:221], v[222:225], v[50:65]
	v_mfma_f32_32x32x16_bf16 v[34:49], v[218:221], v[226:229], v[34:49]
	v_mfma_f32_32x32x16_bf16 v[18:33], v[230:233], v[222:225], v[18:33]
	v_mfma_f32_32x32x16_bf16 v[2:17], v[230:233], v[226:229], v[2:17]
	s_setprio 0
	s_waitcnt vmcnt(8)
	ds_write_b128 v188, v[86:89]
	ds_write_b128 v188, v[98:101] offset:4608
	ds_write_b128 v188, v[102:105] offset:9216
	ds_write_b128 v188, v[110:113] offset:13824
	ds_write_b128 v188, v[114:117] offset:18432
	ds_write_b128 v188, v[118:121] offset:23040
	ds_write_b128 v188, v[122:125] offset:27648
	ds_write_b128 v188, v[126:129] offset:32256
	s_waitcnt lgkmcnt(0)
	s_barrier
	s_setprio 1
	ds_read_b128 v[198:201], v140
	ds_read_b128 v[202:205], v141 offset:18432
	ds_read_b128 v[206:209], v141 offset:23040
	ds_read_b128 v[214:217], v140 offset:4608
	ds_read_b128 v[218:221], v140 offset:32
	ds_read_b128 v[222:225], v141 offset:18464
	ds_read_b128 v[226:229], v141 offset:23072
	ds_read_b128 v[230:233], v140 offset:4640
	s_waitcnt lgkmcnt(4)
	v_mfma_f32_32x32x16_bf16 v[50:65], v[198:201], v[202:205], v[50:65]
	v_mfma_f32_32x32x16_bf16 v[34:49], v[198:201], v[206:209], v[34:49]
	v_mfma_f32_32x32x16_bf16 v[18:33], v[214:217], v[202:205], v[18:33]
	v_mfma_f32_32x32x16_bf16 v[2:17], v[214:217], v[206:209], v[2:17]
	ds_read_b128 v[198:201], v140 offset:64
	ds_read_b128 v[202:205], v141 offset:18496
	ds_read_b128 v[206:209], v141 offset:23104
	ds_read_b128 v[214:217], v140 offset:4672
	s_waitcnt lgkmcnt(4)
	v_mfma_f32_32x32x16_bf16 v[50:65], v[218:221], v[222:225], v[50:65]
	v_mfma_f32_32x32x16_bf16 v[34:49], v[218:221], v[226:229], v[34:49]
	v_mfma_f32_32x32x16_bf16 v[18:33], v[230:233], v[222:225], v[18:33]
	v_mfma_f32_32x32x16_bf16 v[2:17], v[230:233], v[226:229], v[2:17]
	ds_read_b128 v[218:221], v140 offset:96
	ds_read_b128 v[222:225], v141 offset:18528
	ds_read_b128 v[226:229], v141 offset:23136
	ds_read_b128 v[230:233], v140 offset:4704
	s_waitcnt lgkmcnt(4)
	v_mfma_f32_32x32x16_bf16 v[50:65], v[198:201], v[202:205], v[50:65]
	v_mfma_f32_32x32x16_bf16 v[34:49], v[198:201], v[206:209], v[34:49]
	v_mfma_f32_32x32x16_bf16 v[18:33], v[214:217], v[202:205], v[18:33]
	v_mfma_f32_32x32x16_bf16 v[2:17], v[214:217], v[206:209], v[2:17]
	global_load_dwordx4 v[86:89], v[160:161], off offset:1024
	global_load_dwordx4 v[98:101], v[162:163], off offset:1024
	global_load_dwordx4 v[102:105], v[164:165], off offset:1024
	global_load_dwordx4 v[110:113], v[166:167], off offset:1024
	global_load_dwordx4 v[114:117], v[158:159], off offset:1024
	global_load_dwordx4 v[118:121], v[168:169], off offset:1024
	global_load_dwordx4 v[122:125], v[170:171], off offset:1024
	global_load_dwordx4 v[126:129], v[172:173], off offset:1024
	s_waitcnt lgkmcnt(0)
	v_mfma_f32_32x32x16_bf16 v[50:65], v[218:221], v[222:225], v[50:65]
	v_mfma_f32_32x32x16_bf16 v[34:49], v[218:221], v[226:229], v[34:49]
	v_mfma_f32_32x32x16_bf16 v[18:33], v[230:233], v[222:225], v[18:33]
	v_mfma_f32_32x32x16_bf16 v[2:17], v[230:233], v[226:229], v[2:17]
	s_setprio 0
	s_waitcnt vmcnt(8)
	ds_write_b128 v188, v[66:69] offset:36864
	ds_write_b128 v188, v[70:73] offset:41472
	ds_write_b128 v188, v[74:77] offset:46080
	ds_write_b128 v188, v[78:81] offset:50688
	ds_write_b128 v188, v[82:85] offset:55296
	ds_write_b128 v188, v[90:93] offset:59904
	ds_write_b128 v188, v[94:97] offset:64512
	ds_write_b128 v189, v[106:109] offset:13824
	s_waitcnt lgkmcnt(0)
	s_barrier
; __device__ __forceinline__ void gemm_kstep(const u16* sb, int wn, int wt, int r, int h, f32x16 (&acc)[2][2]) {
;   const u16* bw = sb + (wn * 64 + r) * LDT + h * 8;
;   const u16* bx = sb + TILE_U16 + (wt * 64 + r) * LDT + h * 8;
;   __builtin_amdgcn_s_setprio(1);
; #pragma unroll
;   for (int ks = 0; ks < 4; ++ks) {
;     bf16x8 a0 = *(const bf16x8*)(bw + ks * 16);
;     bf16x8 a1 = *(const bf16x8*)(bw + 32 * LDT + ks * 16);
;     bf16x8 b0 = *(const bf16x8*)(bx + ks * 16);
;     bf16x8 b1 = *(const bf16x8*)(bx + 32 * LDT + ks * 16);
;     acc[0][0] = mfma32(a0, b0, acc[0][0]);
;     acc[0][1] = mfma32(a0, b1, acc[0][1]);
;     acc[1][0] = mfma32(a1, b0, acc[1][0]);
;     acc[1][1] = mfma32(a1, b1, acc[1][1]);
;   }
;   __builtin_amdgcn_s_setprio(0);
; }
; __device__ void gemm_phase(const u16* __restrict__ Wb, int ldw, const u16* __restrict__ Xb, int ldx, int K,
;                            u16* __restrict__ outb, int ldo, int ntn, int ntiles, u16* lds) {
;     ...
;     for (int kt = 0; kt < nk; kt += 2) {
;       if (kt + 2 < nk) gs_load(B, gw, ldw, gx, ldx, (kt + 2) * 64);
;       else if (has_next) gs_load(B, gwn, ldw, gxn, ldx, 0);
;       gemm_kstep(lds, wn, wt, r, h, acc);
;       gs_store(A, lds + 2 * TILE_U16, lo);
;       __syncthreads();
;       if (kt + 3 < nk) gs_load(A, gw, ldw, gx, ldx, (kt + 3) * 64);
;       else if (has_next) gs_load(A, gwn, ldw, gxn, ldx, 64);
;       gemm_kstep(lds + 2 * TILE_U16, wn, wt, r, h, acc);
;       if (kt + 2 < nk) gs_store(B, lds, lo);
;       __syncthreads();
;     }
	s_setprio 1
	ds_read_b128 v[198:201], v140 offset:36864
	ds_read_b128 v[202:205], v141 offset:55296
	ds_read_b128 v[206:209], v141 offset:59904
	ds_read_b128 v[214:217], v140 offset:41472
	ds_read_b128 v[218:221], v140 offset:36896
	ds_read_b128 v[222:225], v141 offset:55328
	ds_read_b128 v[226:229], v141 offset:59936
	ds_read_b128 v[230:233], v140 offset:41504
	s_waitcnt lgkmcnt(4)
	v_mfma_f32_32x32x16_bf16 v[50:65], v[198:201], v[202:205], v[50:65]
	v_mfma_f32_32x32x16_bf16 v[34:49], v[198:201], v[206:209], v[34:49]
	v_mfma_f32_32x32x16_bf16 v[18:33], v[214:217], v[202:205], v[18:33]
	v_mfma_f32_32x32x16_bf16 v[2:17], v[214:217], v[206:209], v[2:17]
	ds_read_b128 v[198:201], v140 offset:36928
	ds_read_b128 v[202:205], v141 offset:55360
	ds_read_b128 v[206:209], v141 offset:59968
	ds_read_b128 v[214:217], v140 offset:41536
	s_waitcnt lgkmcnt(4)
	v_mfma_f32_32x32x16_bf16 v[50:65], v[218:221], v[222:225], v[50:65]
	v_mfma_f32_32x32x16_bf16 v[34:49], v[218:221], v[226:229], v[34:49]
	v_mfma_f32_32x32x16_bf16 v[18:33], v[230:233], v[222:225], v[18:33]
	v_mfma_f32_32x32x16_bf16 v[2:17], v[230:233], v[226:229], v[2:17]
	ds_read_b128 v[218:221], v140 offset:36960
	ds_read_b128 v[222:225], v141 offset:55392
	ds_read_b128 v[226:229], v141 offset:60000
	ds_read_b128 v[230:233], v140 offset:41568
	s_waitcnt lgkmcnt(4)
	v_mfma_f32_32x32x16_bf16 v[50:65], v[198:201], v[202:205], v[50:65]
	v_mfma_f32_32x32x16_bf16 v[34:49], v[198:201], v[206:209], v[34:49]
	v_mfma_f32_32x32x16_bf16 v[18:33], v[214:217], v[202:205], v[18:33]
	v_mfma_f32_32x32x16_bf16 v[2:17], v[214:217], v[206:209], v[2:17]
	global_load_dwordx4 v[66:69], v[160:161], off offset:1152
	global_load_dwordx4 v[70:73], v[162:163], off offset:1152
	global_load_dwordx4 v[74:77], v[164:165], off offset:1152
	global_load_dwordx4 v[78:81], v[166:167], off offset:1152
	global_load_dwordx4 v[82:85], v[158:159], off offset:1152
	global_load_dwordx4 v[90:93], v[168:169], off offset:1152
	global_load_dwordx4 v[94:97], v[170:171], off offset:1152
	global_load_dwordx4 v[106:109], v[172:173], off offset:1152
	s_waitcnt lgkmcnt(0)
	v_mfma_f32_32x32x16_bf16 v[50:65], v[218:221], v[222:225], v[50:65]
	v_mfma_f32_32x32x16_bf16 v[34:49], v[218:221], v[226:229], v[34:49]
	v_mfma_f32_32x32x16_bf16 v[18:33], v[230:233], v[222:225], v[18:33]
	v_mfma_f32_32x32x16_bf16 v[2:17], v[230:233], v[226:229], v[2:17]
	s_setprio 0
	s_waitcnt vmcnt(8)
	ds_write_b128 v188, v[86:89]
	ds_write_b128 v188, v[98:101] offset:4608
	ds_write_b128 v188, v[102:105] offset:9216
	ds_write_b128 v188, v[110:113] offset:13824
	ds_write_b128 v188, v[114:117] offset:18432
	ds_write_b128 v188, v[118:121] offset:23040
	ds_write_b128 v188, v[122:125] offset:27648
	ds_write_b128 v188, v[126:129] offset:32256
	s_waitcnt lgkmcnt(0)
	s_barrier
	s_setprio 1
	ds_read_b128 v[198:201], v140
	ds_read_b128 v[202:205], v141 offset:18432
	ds_read_b128 v[206:209], v141 offset:23040
	ds_read_b128 v[214:217], v140 offset:4608
	ds_read_b128 v[218:221], v140 offset:32
	ds_read_b128 v[222:225], v141 offset:18464
	ds_read_b128 v[226:229], v141 offset:23072
	ds_read_b128 v[230:233], v140 offset:4640
	s_waitcnt lgkmcnt(4)
	v_mfma_f32_32x32x16_bf16 v[50:65], v[198:201], v[202:205], v[50:65]
	v_mfma_f32_32x32x16_bf16 v[34:49], v[198:201], v[206:209], v[34:49]
	v_mfma_f32_32x32x16_bf16 v[18:33], v[214:217], v[202:205], v[18:33]
	v_mfma_f32_32x32x16_bf16 v[2:17], v[214:217], v[206:209], v[2:17]
	ds_read_b128 v[198:201], v140 offset:64
	ds_read_b128 v[202:205], v141 offset:18496
	ds_read_b128 v[206:209], v141 offset:23104
	ds_read_b128 v[214:217], v140 offset:4672
	s_waitcnt lgkmcnt(4)
	v_mfma_f32_32x32x16_bf16 v[50:65], v[218:221], v[222:225], v[50:65]
	v_mfma_f32_32x32x16_bf16 v[34:49], v[218:221], v[226:229], v[34:49]
	v_mfma_f32_32x32x16_bf16 v[18:33], v[230:233], v[222:225], v[18:33]
	v_mfma_f32_32x32x16_bf16 v[2:17], v[230:233], v[226:229], v[2:17]
	ds_read_b128 v[218:221], v140 offset:96
	ds_read_b128 v[222:225], v141 offset:18528
	ds_read_b128 v[226:229], v141 offset:23136
	ds_read_b128 v[230:233], v140 offset:4704
	s_waitcnt lgkmcnt(4)
	v_mfma_f32_32x32x16_bf16 v[50:65], v[198:201], v[202:205], v[50:65]
	v_mfma_f32_32x32x16_bf16 v[34:49], v[198:201], v[206:209], v[34:49]
	v_mfma_f32_32x32x16_bf16 v[18:33], v[214:217], v[202:205], v[18:33]
	v_mfma_f32_32x32x16_bf16 v[2:17], v[214:217], v[206:209], v[2:17]
	global_load_dwordx4 v[86:89], v[160:161], off offset:1280
	global_load_dwordx4 v[98:101], v[162:163], off offset:1280
	global_load_dwordx4 v[102:105], v[164:165], off offset:1280
	global_load_dwordx4 v[110:113], v[166:167], off offset:1280
	global_load_dwordx4 v[114:117], v[158:159], off offset:1280
	global_load_dwordx4 v[118:121], v[168:169], off offset:1280
	global_load_dwordx4 v[122:125], v[170:171], off offset:1280
	global_load_dwordx4 v[126:129], v[172:173], off offset:1280
	s_waitcnt lgkmcnt(0)
	v_mfma_f32_32x32x16_bf16 v[50:65], v[218:221], v[222:225], v[50:65]
	v_mfma_f32_32x32x16_bf16 v[34:49], v[218:221], v[226:229], v[34:49]
	v_mfma_f32_32x32x16_bf16 v[18:33], v[230:233], v[222:225], v[18:33]
	v_mfma_f32_32x32x16_bf16 v[2:17], v[230:233], v[226:229], v[2:17]
	s_setprio 0
	s_waitcnt vmcnt(8)
	ds_write_b128 v188, v[66:69] offset:36864
	ds_write_b128 v188, v[70:73] offset:41472
	ds_write_b128 v188, v[74:77] offset:46080
	ds_write_b128 v188, v[78:81] offset:50688
	ds_write_b128 v188, v[82:85] offset:55296
	ds_write_b128 v188, v[90:93] offset:59904
	ds_write_b128 v188, v[94:97] offset:64512
	ds_write_b128 v189, v[106:109] offset:13824
	s_waitcnt lgkmcnt(0)
	s_barrier
; __device__ __forceinline__ void gemm_kstep(const u16* sb, int wn, int wt, int r, int h, f32x16 (&acc)[2][2]) {
;   const u16* bw = sb + (wn * 64 + r) * LDT + h * 8;
;   const u16* bx = sb + TILE_U16 + (wt * 64 + r) * LDT + h * 8;
;   __builtin_amdgcn_s_setprio(1);
; #pragma unroll
;   for (int ks = 0; ks < 4; ++ks) {
;     bf16x8 a0 = *(const bf16x8*)(bw + ks * 16);
;     bf16x8 a1 = *(const bf16x8*)(bw + 32 * LDT + ks * 16);
;     bf16x8 b0 = *(const bf16x8*)(bx + ks * 16);
;     bf16x8 b1 = *(const bf16x8*)(bx + 32 * LDT + ks * 16);
;     acc[0][0] = mfma32(a0, b0, acc[0][0]);
;     acc[0][1] = mfma32(a0, b1, acc[0][1]);
;     acc[1][0] = mfma32(a1, b0, acc[1][0]);
;     acc[1][1] = mfma32(a1, b1, acc[1][1]);
;   }
;   __builtin_amdgcn_s_setprio(0);
; }
; __device__ void gemm_phase(const u16* __restrict__ Wb, int ldw, const u16* __restrict__ Xb, int ldx, int K,
;                            u16* __restrict__ outb, int ldo, int ntn, int ntiles, u16* lds) {
;     ...
;     for (int kt = 0; kt < nk; kt += 2) {
;       if (kt + 2 < nk) gs_load(B, gw, ldw, gx, ldx, (kt + 2) * 64);
;       else if (has_next) gs_load(B, gwn, ldw, gxn, ldx, 0);
;       gemm_kstep(lds, wn, wt, r, h, acc);
;       gs_store(A, lds + 2 * TILE_U16, lo);
;       __syncthreads();
;       if (kt + 3 < nk) gs_load(A, gw, ldw, gx, ldx, (kt + 3) * 64);
;       else if (has_next) gs_load(A, gwn, ldw, gxn, ldx, 64);
;       gemm_kstep(lds + 2 * TILE_U16, wn, wt, r, h, acc);
;       if (kt + 2 < nk) gs_store(B, lds, lo);
;       __syncthreads();
;     }
	s_setprio 1
	ds_read_b128 v[198:201], v140 offset:36864
	ds_read_b128 v[202:205], v141 offset:55296
	ds_read_b128 v[206:209], v141 offset:59904
	ds_read_b128 v[214:217], v140 offset:41472
	ds_read_b128 v[218:221], v140 offset:36896
	ds_read_b128 v[222:225], v141 offset:55328
	ds_read_b128 v[226:229], v141 offset:59936
	ds_read_b128 v[230:233], v140 offset:41504
	s_waitcnt lgkmcnt(4)
	v_mfma_f32_32x32x16_bf16 v[50:65], v[198:201], v[202:205], v[50:65]
	v_mfma_f32_32x32x16_bf16 v[34:49], v[198:201], v[206:209], v[34:49]
	v_mfma_f32_32x32x16_bf16 v[18:33], v[214:217], v[202:205], v[18:33]
	v_mfma_f32_32x32x16_bf16 v[2:17], v[214:217], v[206:209], v[2:17]
	ds_read_b128 v[198:201], v140 offset:36928
	ds_read_b128 v[202:205], v141 offset:55360
	ds_read_b128 v[206:209], v141 offset:59968
	ds_read_b128 v[214:217], v140 offset:41536
	s_waitcnt lgkmcnt(4)
	v_mfma_f32_32x32x16_bf16 v[50:65], v[218:221], v[222:225], v[50:65]
	v_mfma_f32_32x32x16_bf16 v[34:49], v[218:221], v[226:229], v[34:49]
	v_mfma_f32_32x32x16_bf16 v[18:33], v[230:233], v[222:225], v[18:33]
	v_mfma_f32_32x32x16_bf16 v[2:17], v[230:233], v[226:229], v[2:17]
	ds_read_b128 v[218:221], v140 offset:36960
	ds_read_b128 v[222:225], v141 offset:55392
	ds_read_b128 v[226:229], v141 offset:60000
	ds_read_b128 v[230:233], v140 offset:41568
	s_waitcnt lgkmcnt(4)
	v_mfma_f32_32x32x16_bf16 v[50:65], v[198:201], v[202:205], v[50:65]
	v_mfma_f32_32x32x16_bf16 v[34:49], v[198:201], v[206:209], v[34:49]
	v_mfma_f32_32x32x16_bf16 v[18:33], v[214:217], v[202:205], v[18:33]
	v_mfma_f32_32x32x16_bf16 v[2:17], v[214:217], v[206:209], v[2:17]
	global_load_dwordx4 v[66:69], v[160:161], off offset:1408
	global_load_dwordx4 v[70:73], v[162:163], off offset:1408
	global_load_dwordx4 v[74:77], v[164:165], off offset:1408
	global_load_dwordx4 v[78:81], v[166:167], off offset:1408
	global_load_dwordx4 v[82:85], v[158:159], off offset:1408
	global_load_dwordx4 v[90:93], v[168:169], off offset:1408
	global_load_dwordx4 v[94:97], v[170:171], off offset:1408
	global_load_dwordx4 v[106:109], v[172:173], off offset:1408
	s_waitcnt lgkmcnt(0)
	v_mfma_f32_32x32x16_bf16 v[50:65], v[218:221], v[222:225], v[50:65]
	v_mfma_f32_32x32x16_bf16 v[34:49], v[218:221], v[226:229], v[34:49]
	v_mfma_f32_32x32x16_bf16 v[18:33], v[230:233], v[222:225], v[18:33]
	v_mfma_f32_32x32x16_bf16 v[2:17], v[230:233], v[226:229], v[2:17]
	s_setprio 0
	s_waitcnt vmcnt(8)
	ds_write_b128 v188, v[86:89]
	ds_write_b128 v188, v[98:101] offset:4608
	ds_write_b128 v188, v[102:105] offset:9216
	ds_write_b128 v188, v[110:113] offset:13824
	ds_write_b128 v188, v[114:117] offset:18432
	ds_write_b128 v188, v[118:121] offset:23040
	ds_write_b128 v188, v[122:125] offset:27648
	ds_write_b128 v188, v[126:129] offset:32256
	s_waitcnt lgkmcnt(0)
	s_barrier
	s_setprio 1
	ds_read_b128 v[198:201], v140
	ds_read_b128 v[202:205], v141 offset:18432
	ds_read_b128 v[206:209], v141 offset:23040
	ds_read_b128 v[214:217], v140 offset:4608
	ds_read_b128 v[218:221], v140 offset:32
	ds_read_b128 v[222:225], v141 offset:18464
	ds_read_b128 v[226:229], v141 offset:23072
	ds_read_b128 v[230:233], v140 offset:4640
	s_waitcnt lgkmcnt(4)
	v_mfma_f32_32x32x16_bf16 v[50:65], v[198:201], v[202:205], v[50:65]
	v_mfma_f32_32x32x16_bf16 v[34:49], v[198:201], v[206:209], v[34:49]
	v_mfma_f32_32x32x16_bf16 v[18:33], v[214:217], v[202:205], v[18:33]
	v_mfma_f32_32x32x16_bf16 v[2:17], v[214:217], v[206:209], v[2:17]
	ds_read_b128 v[198:201], v140 offset:64
	ds_read_b128 v[202:205], v141 offset:18496
	ds_read_b128 v[206:209], v141 offset:23104
	ds_read_b128 v[214:217], v140 offset:4672
	s_waitcnt lgkmcnt(4)
	v_mfma_f32_32x32x16_bf16 v[50:65], v[218:221], v[222:225], v[50:65]
	v_mfma_f32_32x32x16_bf16 v[34:49], v[218:221], v[226:229], v[34:49]
	v_mfma_f32_32x32x16_bf16 v[18:33], v[230:233], v[222:225], v[18:33]
	v_mfma_f32_32x32x16_bf16 v[2:17], v[230:233], v[226:229], v[2:17]
	ds_read_b128 v[218:221], v140 offset:96
	ds_read_b128 v[222:225], v141 offset:18528
	ds_read_b128 v[226:229], v141 offset:23136
	ds_read_b128 v[230:233], v140 offset:4704
	s_waitcnt lgkmcnt(4)
	v_mfma_f32_32x32x16_bf16 v[50:65], v[198:201], v[202:205], v[50:65]
	v_mfma_f32_32x32x16_bf16 v[34:49], v[198:201], v[206:209], v[34:49]
	v_mfma_f32_32x32x16_bf16 v[18:33], v[214:217], v[202:205], v[18:33]
	v_mfma_f32_32x32x16_bf16 v[2:17], v[214:217], v[206:209], v[2:17]
	global_load_dwordx4 v[86:89], v[160:161], off offset:1536
	global_load_dwordx4 v[98:101], v[162:163], off offset:1536
	global_load_dwordx4 v[102:105], v[164:165], off offset:1536
	global_load_dwordx4 v[110:113], v[166:167], off offset:1536
	global_load_dwordx4 v[114:117], v[158:159], off offset:1536
	global_load_dwordx4 v[118:121], v[168:169], off offset:1536
	global_load_dwordx4 v[122:125], v[170:171], off offset:1536
	global_load_dwordx4 v[126:129], v[172:173], off offset:1536
	s_waitcnt lgkmcnt(0)
	v_mfma_f32_32x32x16_bf16 v[50:65], v[218:221], v[222:225], v[50:65]
	v_mfma_f32_32x32x16_bf16 v[34:49], v[218:221], v[226:229], v[34:49]
	v_mfma_f32_32x32x16_bf16 v[18:33], v[230:233], v[222:225], v[18:33]
	v_mfma_f32_32x32x16_bf16 v[2:17], v[230:233], v[226:229], v[2:17]
	s_setprio 0
	s_waitcnt vmcnt(8)
	ds_write_b128 v188, v[66:69] offset:36864
	ds_write_b128 v188, v[70:73] offset:41472
	ds_write_b128 v188, v[74:77] offset:46080
	ds_write_b128 v188, v[78:81] offset:50688
	ds_write_b128 v188, v[82:85] offset:55296
	ds_write_b128 v188, v[90:93] offset:59904
	ds_write_b128 v188, v[94:97] offset:64512
	ds_write_b128 v189, v[106:109] offset:13824
	s_waitcnt lgkmcnt(0)
	s_barrier
; __device__ __forceinline__ void gemm_kstep(const u16* sb, int wn, int wt, int r, int h, f32x16 (&acc)[2][2]) {
;   const u16* bw = sb + (wn * 64 + r) * LDT + h * 8;
;   const u16* bx = sb + TILE_U16 + (wt * 64 + r) * LDT + h * 8;
;   __builtin_amdgcn_s_setprio(1);
; #pragma unroll
;   for (int ks = 0; ks < 4; ++ks) {
;     bf16x8 a0 = *(const bf16x8*)(bw + ks * 16);
;     bf16x8 a1 = *(const bf16x8*)(bw + 32 * LDT + ks * 16);
;     bf16x8 b0 = *(const bf16x8*)(bx + ks * 16);
;     bf16x8 b1 = *(const bf16x8*)(bx + 32 * LDT + ks * 16);
;     acc[0][0] = mfma32(a0, b0, acc[0][0]);
;     acc[0][1] = mfma32(a0, b1, acc[0][1]);
;     acc[1][0] = mfma32(a1, b0, acc[1][0]);
;     acc[1][1] = mfma32(a1, b1, acc[1][1]);
;   }
;   __builtin_amdgcn_s_setprio(0);
; }
; __device__ void gemm_phase(const u16* __restrict__ Wb, int ldw, const u16* __restrict__ Xb, int ldx, int K,
;                            u16* __restrict__ outb, int ldo, int ntn, int ntiles, u16* lds) {
;     ...
;     for (int kt = 0; kt < nk; kt += 2) {
;       if (kt + 2 < nk) gs_load(B, gw, ldw, gx, ldx, (kt + 2) * 64);
;       else if (has_next) gs_load(B, gwn, ldw, gxn, ldx, 0);
;       gemm_kstep(lds, wn, wt, r, h, acc);
;       gs_store(A, lds + 2 * TILE_U16, lo);
;       __syncthreads();
;       if (kt + 3 < nk) gs_load(A, gw, ldw, gx, ldx, (kt + 3) * 64);
;       else if (has_next) gs_load(A, gwn, ldw, gxn, ldx, 64);
;       gemm_kstep(lds + 2 * TILE_U16, wn, wt, r, h, acc);
;       if (kt + 2 < nk) gs_store(B, lds, lo);
;       __syncthreads();
;     }
	s_setprio 1
	ds_read_b128 v[198:201], v140 offset:36864
	ds_read_b128 v[202:205], v141 offset:55296
	ds_read_b128 v[206:209], v141 offset:59904
	ds_read_b128 v[214:217], v140 offset:41472
	ds_read_b128 v[218:221], v140 offset:36896
	ds_read_b128 v[222:225], v141 offset:55328
	ds_read_b128 v[226:229], v141 offset:59936
	ds_read_b128 v[230:233], v140 offset:41504
	s_waitcnt lgkmcnt(4)
	v_mfma_f32_32x32x16_bf16 v[50:65], v[198:201], v[202:205], v[50:65]
	v_mfma_f32_32x32x16_bf16 v[34:49], v[198:201], v[206:209], v[34:49]
	v_mfma_f32_32x32x16_bf16 v[18:33], v[214:217], v[202:205], v[18:33]
	v_mfma_f32_32x32x16_bf16 v[2:17], v[214:217], v[206:209], v[2:17]
	ds_read_b128 v[198:201], v140 offset:36928
	ds_read_b128 v[202:205], v141 offset:55360
	ds_read_b128 v[206:209], v141 offset:59968
	ds_read_b128 v[214:217], v140 offset:41536
	s_waitcnt lgkmcnt(4)
	v_mfma_f32_32x32x16_bf16 v[50:65], v[218:221], v[222:225], v[50:65]
	v_mfma_f32_32x32x16_bf16 v[34:49], v[218:221], v[226:229], v[34:49]
	v_mfma_f32_32x32x16_bf16 v[18:33], v[230:233], v[222:225], v[18:33]
	v_mfma_f32_32x32x16_bf16 v[2:17], v[230:233], v[226:229], v[2:17]
	ds_read_b128 v[218:221], v140 offset:36960
	ds_read_b128 v[222:225], v141 offset:55392
	ds_read_b128 v[226:229], v141 offset:60000
	ds_read_b128 v[230:233], v140 offset:41568
	s_waitcnt lgkmcnt(4)
	v_mfma_f32_32x32x16_bf16 v[50:65], v[198:201], v[202:205], v[50:65]
	v_mfma_f32_32x32x16_bf16 v[34:49], v[198:201], v[206:209], v[34:49]
	v_mfma_f32_32x32x16_bf16 v[18:33], v[214:217], v[202:205], v[18:33]
	v_mfma_f32_32x32x16_bf16 v[2:17], v[214:217], v[206:209], v[2:17]
	global_load_dwordx4 v[66:69], v[160:161], off offset:1664
	global_load_dwordx4 v[70:73], v[162:163], off offset:1664
	global_load_dwordx4 v[74:77], v[164:165], off offset:1664
	global_load_dwordx4 v[78:81], v[166:167], off offset:1664
	global_load_dwordx4 v[82:85], v[158:159], off offset:1664
	global_load_dwordx4 v[90:93], v[168:169], off offset:1664
	global_load_dwordx4 v[94:97], v[170:171], off offset:1664
	global_load_dwordx4 v[106:109], v[172:173], off offset:1664
	s_waitcnt lgkmcnt(0)
	v_mfma_f32_32x32x16_bf16 v[50:65], v[218:221], v[222:225], v[50:65]
	v_mfma_f32_32x32x16_bf16 v[34:49], v[218:221], v[226:229], v[34:49]
	v_mfma_f32_32x32x16_bf16 v[18:33], v[230:233], v[222:225], v[18:33]
	v_mfma_f32_32x32x16_bf16 v[2:17], v[230:233], v[226:229], v[2:17]
	s_setprio 0
	s_waitcnt vmcnt(8)
	ds_write_b128 v188, v[86:89]
	ds_write_b128 v188, v[98:101] offset:4608
	ds_write_b128 v188, v[102:105] offset:9216
	ds_write_b128 v188, v[110:113] offset:13824
	ds_write_b128 v188, v[114:117] offset:18432
	ds_write_b128 v188, v[118:121] offset:23040
	ds_write_b128 v188, v[122:125] offset:27648
	ds_write_b128 v188, v[126:129] offset:32256
	s_waitcnt lgkmcnt(0)
	s_barrier
	s_setprio 1
	ds_read_b128 v[198:201], v140
	ds_read_b128 v[202:205], v141 offset:18432
	ds_read_b128 v[206:209], v141 offset:23040
	ds_read_b128 v[214:217], v140 offset:4608
	ds_read_b128 v[218:221], v140 offset:32
	ds_read_b128 v[222:225], v141 offset:18464
	ds_read_b128 v[226:229], v141 offset:23072
	ds_read_b128 v[230:233], v140 offset:4640
	s_waitcnt lgkmcnt(4)
	v_mfma_f32_32x32x16_bf16 v[50:65], v[198:201], v[202:205], v[50:65]
	v_mfma_f32_32x32x16_bf16 v[34:49], v[198:201], v[206:209], v[34:49]
	v_mfma_f32_32x32x16_bf16 v[18:33], v[214:217], v[202:205], v[18:33]
	v_mfma_f32_32x32x16_bf16 v[2:17], v[214:217], v[206:209], v[2:17]
	ds_read_b128 v[198:201], v140 offset:64
	ds_read_b128 v[202:205], v141 offset:18496
	ds_read_b128 v[206:209], v141 offset:23104
	ds_read_b128 v[214:217], v140 offset:4672
	s_waitcnt lgkmcnt(4)
	v_mfma_f32_32x32x16_bf16 v[50:65], v[218:221], v[222:225], v[50:65]
	v_mfma_f32_32x32x16_bf16 v[34:49], v[218:221], v[226:229], v[34:49]
	v_mfma_f32_32x32x16_bf16 v[18:33], v[230:233], v[222:225], v[18:33]
	v_mfma_f32_32x32x16_bf16 v[2:17], v[230:233], v[226:229], v[2:17]
	ds_read_b128 v[218:221], v140 offset:96
	ds_read_b128 v[222:225], v141 offset:18528
	ds_read_b128 v[226:229], v141 offset:23136
	ds_read_b128 v[230:233], v140 offset:4704
	s_waitcnt lgkmcnt(4)
	v_mfma_f32_32x32x16_bf16 v[50:65], v[198:201], v[202:205], v[50:65]
	v_mfma_f32_32x32x16_bf16 v[34:49], v[198:201], v[206:209], v[34:49]
	v_mfma_f32_32x32x16_bf16 v[18:33], v[214:217], v[202:205], v[18:33]
	v_mfma_f32_32x32x16_bf16 v[2:17], v[214:217], v[206:209], v[2:17]
	global_load_dwordx4 v[86:89], v[160:161], off offset:1792
	global_load_dwordx4 v[98:101], v[162:163], off offset:1792
	global_load_dwordx4 v[102:105], v[164:165], off offset:1792
	global_load_dwordx4 v[110:113], v[166:167], off offset:1792
	global_load_dwordx4 v[114:117], v[158:159], off offset:1792
	global_load_dwordx4 v[118:121], v[168:169], off offset:1792
	global_load_dwordx4 v[122:125], v[170:171], off offset:1792
	global_load_dwordx4 v[126:129], v[172:173], off offset:1792
	s_waitcnt lgkmcnt(0)
	v_mfma_f32_32x32x16_bf16 v[50:65], v[218:221], v[222:225], v[50:65]
	v_mfma_f32_32x32x16_bf16 v[34:49], v[218:221], v[226:229], v[34:49]
	v_mfma_f32_32x32x16_bf16 v[18:33], v[230:233], v[222:225], v[18:33]
	v_mfma_f32_32x32x16_bf16 v[2:17], v[230:233], v[226:229], v[2:17]
	s_setprio 0
	s_waitcnt vmcnt(8)
	ds_write_b128 v188, v[66:69] offset:36864
	ds_write_b128 v188, v[70:73] offset:41472
	ds_write_b128 v188, v[74:77] offset:46080
	ds_write_b128 v188, v[78:81] offset:50688
	ds_write_b128 v188, v[82:85] offset:55296
	ds_write_b128 v188, v[90:93] offset:59904
	ds_write_b128 v188, v[94:97] offset:64512
	ds_write_b128 v189, v[106:109] offset:13824
	s_waitcnt lgkmcnt(0)
	s_barrier
; __device__ __forceinline__ void gemm_kstep(const u16* sb, int wn, int wt, int r, int h, f32x16 (&acc)[2][2]) {
;   const u16* bw = sb + (wn * 64 + r) * LDT + h * 8;
;   const u16* bx = sb + TILE_U16 + (wt * 64 + r) * LDT + h * 8;
;   __builtin_amdgcn_s_setprio(1);
; #pragma unroll
;   for (int ks = 0; ks < 4; ++ks) {
;     bf16x8 a0 = *(const bf16x8*)(bw + ks * 16);
;     bf16x8 a1 = *(const bf16x8*)(bw + 32 * LDT + ks * 16);
;     bf16x8 b0 = *(const bf16x8*)(bx + ks * 16);
;     bf16x8 b1 = *(const bf16x8*)(bx + 32 * LDT + ks * 16);
;     acc[0][0] = mfma32(a0, b0, acc[0][0]);
;     acc[0][1] = mfma32(a0, b1, acc[0][1]);
;     acc[1][0] = mfma32(a1, b0, acc[1][0]);
;     acc[1][1] = mfma32(a1, b1, acc[1][1]);
;   }
;   __builtin_amdgcn_s_setprio(0);
; }
; __device__ void gemm_phase(const u16* __restrict__ Wb, int ldw, const u16* __restrict__ Xb, int ldx, int K,
;                            u16* __restrict__ outb, int ldo, int ntn, int ntiles, u16* lds) {
;     ...
;     for (int kt = 0; kt < nk; kt += 2) {
;       if (kt + 2 < nk) gs_load(B, gw, ldw, gx, ldx, (kt + 2) * 64);
;       else if (has_next) gs_load(B, gwn, ldw, gxn, ldx, 0);
;       gemm_kstep(lds, wn, wt, r, h, acc);
;       gs_store(A, lds + 2 * TILE_U16, lo);
;       __syncthreads();
;       if (kt + 3 < nk) gs_load(A, gw, ldw, gx, ldx, (kt + 3) * 64);
;       else if (has_next) gs_load(A, gwn, ldw, gxn, ldx, 64);
;       gemm_kstep(lds + 2 * TILE_U16, wn, wt, r, h, acc);
;       if (kt + 2 < nk) gs_store(B, lds, lo);
;       __syncthreads();
;     }
	global_load_dwordx4 v[66:69], v[160:161], off offset:1920
	global_load_dwordx4 v[70:73], v[162:163], off offset:1920
	global_load_dwordx4 v[74:77], v[164:165], off offset:1920
	global_load_dwordx4 v[78:81], v[166:167], off offset:1920
	global_load_dwordx4 v[82:85], v[158:159], off offset:1920
	global_load_dwordx4 v[90:93], v[168:169], off offset:1920
	global_load_dwordx4 v[94:97], v[170:171], off offset:1920
	global_load_dwordx4 v[106:109], v[172:173], off offset:1920
	s_setprio 1
	ds_read_b128 v[158:161], v140 offset:36864
	ds_read_b128 v[162:165], v141 offset:55296
	ds_read_b128 v[166:169], v141 offset:59904
	ds_read_b128 v[214:217], v140 offset:41472
	ds_read_b128 v[218:221], v140 offset:36896
	ds_read_b128 v[222:225], v141 offset:55328
	ds_read_b128 v[226:229], v141 offset:59936
	ds_read_b128 v[230:233], v140 offset:41504
	s_waitcnt lgkmcnt(4)
	v_mfma_f32_32x32x16_bf16 v[50:65], v[158:161], v[162:165], v[50:65]
	v_mfma_f32_32x32x16_bf16 v[34:49], v[158:161], v[166:169], v[34:49]
	v_mfma_f32_32x32x16_bf16 v[18:33], v[214:217], v[162:165], v[18:33]
	v_mfma_f32_32x32x16_bf16 v[2:17], v[214:217], v[166:169], v[2:17]
	ds_read_b128 v[158:161], v140 offset:36928
	ds_read_b128 v[162:165], v141 offset:55360
	ds_read_b128 v[166:169], v141 offset:59968
	ds_read_b128 v[214:217], v140 offset:41536
	s_waitcnt lgkmcnt(4)
	v_mfma_f32_32x32x16_bf16 v[50:65], v[218:221], v[222:225], v[50:65]
	v_mfma_f32_32x32x16_bf16 v[34:49], v[218:221], v[226:229], v[34:49]
	v_mfma_f32_32x32x16_bf16 v[18:33], v[230:233], v[222:225], v[18:33]
	v_mfma_f32_32x32x16_bf16 v[2:17], v[230:233], v[226:229], v[2:17]
	ds_read_b128 v[218:221], v140 offset:36960
	ds_read_b128 v[222:225], v141 offset:55392
	ds_read_b128 v[226:229], v141 offset:60000
	ds_read_b128 v[230:233], v140 offset:41568
	s_waitcnt lgkmcnt(4)
	v_mfma_f32_32x32x16_bf16 v[50:65], v[158:161], v[162:165], v[50:65]
	v_mfma_f32_32x32x16_bf16 v[34:49], v[158:161], v[166:169], v[34:49]
	v_mfma_f32_32x32x16_bf16 v[18:33], v[214:217], v[162:165], v[18:33]
	v_mfma_f32_32x32x16_bf16 v[2:17], v[214:217], v[166:169], v[2:17]
	s_waitcnt lgkmcnt(0)
	v_mfma_f32_32x32x16_bf16 v[50:65], v[218:221], v[222:225], v[50:65]
	v_mfma_f32_32x32x16_bf16 v[34:49], v[218:221], v[226:229], v[34:49]
	v_mfma_f32_32x32x16_bf16 v[18:33], v[230:233], v[222:225], v[18:33]
	v_mfma_f32_32x32x16_bf16 v[2:17], v[230:233], v[226:229], v[2:17]
	s_setprio 0
	s_and_b64 vcc, exec, s[0:1]
	s_waitcnt vmcnt(8)
	ds_write_b128 v188, v[86:89]
	ds_write_b128 v188, v[98:101] offset:4608
	ds_write_b128 v188, v[102:105] offset:9216
	ds_write_b128 v188, v[110:113] offset:13824
	ds_write_b128 v188, v[114:117] offset:18432
	ds_write_b128 v188, v[118:121] offset:23040
	ds_write_b128 v188, v[122:125] offset:27648
	ds_write_b128 v188, v[126:129] offset:32256
	s_waitcnt lgkmcnt(0)
	s_barrier
	s_cbranch_vccnz .LBB0_611
	v_add_co_u32_e32 v98, vcc, 0x10000, v132
	global_load_dwordx4 v[86:89], v[132:133], off
	s_nop 0
	v_addc_co_u32_e32 v99, vcc, 0, v133, vcc
	v_add_co_u32_e32 v102, vcc, 0x20000, v132
	s_nop 1
	v_addc_co_u32_e32 v103, vcc, 0, v133, vcc
	v_add_co_u32_e32 v110, vcc, 0x30000, v132
	global_load_dwordx4 v[98:101], v[98:99], off
	s_nop 0
	global_load_dwordx4 v[102:105], v[102:103], off
	v_addc_co_u32_e32 v111, vcc, 0, v133, vcc
	v_add_co_u32_e32 v118, vcc, 0x10000, v134
	global_load_dwordx4 v[110:113], v[110:111], off
	s_nop 0
	global_load_dwordx4 v[114:117], v[134:135], off
	v_addc_co_u32_e32 v119, vcc, 0, v135, vcc
	v_add_co_u32_e32 v122, vcc, 0x20000, v134
	s_nop 1
	v_addc_co_u32_e32 v123, vcc, 0, v135, vcc
	v_add_co_u32_e32 v126, vcc, 0x30000, v134
	global_load_dwordx4 v[118:121], v[118:119], off
	s_nop 0
	global_load_dwordx4 v[122:125], v[122:123], off
	v_addc_co_u32_e32 v127, vcc, 0, v135, vcc
	global_load_dwordx4 v[126:129], v[126:127], off
